# attention softmax uses plain v_exp_f32 instead of the denormal-range exp2 expansion
# speedup vs baseline: 1.0782x; 1.0019x over previous
; #define LAS __attribute__((address_space(3)))
; __device__ void attn_mfma(const Params& p, int l, const bf16_t* proj, bf16_t* y0, LAS unsigned char* lds) {
;     ...
;         for (int tile = 0; tile < 4; ++tile) {
;             const int tl = (wv & 1) * 64 + tile * 16 + fr, t = n * 128 + tl;
;             bf16x8 qf[2];
; #pragma unroll
;             for (int ks = 0; ks < 2; ++ks) { qf[ks] = qn[ks]; qn[ks] = *(const bf16x8*)(proj + (size_t)(t + (tile < 3 ? 16 : 0)) * NP + AQ + hq * 64 + ks * 32 + g * 8); }
;             f32x4 sacc[24];
; #pragma unroll
;             for (int kt = 0; kt < 24; ++kt) { f32x4 a = {0.f, 0.f, 0.f, 0.f};
; #pragma unroll
;                 for (int ks = 0; ks < 2; ++ks) { const bf16x8 kf = *(const LAS bf16x8*)(Ks + (kt * 16 + fr) * KP + ks * 32 + g * 8); a = __builtin_amdgcn_mfma_f32_16x16x32_bf16(kf, qf[ks], a, 0, 0, 0); }
;                 sacc[kt] = a; if ((kt % 6) == 5) __builtin_amdgcn_sched_barrier(0); }
.LBB0_478:
	ds_read_b128 v[0:3], v141
	ds_read_b128 v[4:7], v141 offset:64
	ds_read_b128 v[12:15], v141 offset:2304
	ds_read_b128 v[16:19], v141 offset:2368
	s_cmp_eq_u32 s12, 48
	v_add_u32_e32 v118, s12, v148
	s_waitcnt vmcnt(2) lgkmcnt(3)
	v_mfma_f32_16x16x32_bf16 v[0:3], v[0:3], v[100:103], 0
	s_cselect_b32 s13, 0, 16
	v_add_u32_e32 v22, s13, v118
	v_mov_b64_e32 v[20:21], s[94:95]
	s_waitcnt lgkmcnt(1)
	v_mfma_f32_16x16x32_bf16 v[12:15], v[12:15], v[100:103], 0
	s_waitcnt vmcnt(1)
	v_mfma_f32_16x16x32_bf16 v[104:107], v[4:7], v[8:11], v[0:3]
	ds_read_b128 v[4:7], v141 offset:4672
	s_nop 1
	ds_read_b128 v[0:3], v141 offset:4608
	s_waitcnt lgkmcnt(2)
	v_mfma_f32_16x16x32_bf16 v[96:99], v[16:19], v[8:11], v[12:15]
	ds_read_b128 v[16:19], v141 offset:6976
	s_nop 1
	ds_read_b128 v[12:15], v141 offset:6912
	s_waitcnt lgkmcnt(2)
	v_mfma_f32_16x16x32_bf16 v[0:3], v[0:3], v[100:103], 0
	v_mfma_f32_16x16x32_bf16 v[92:95], v[4:7], v[8:11], v[0:3]
	s_waitcnt lgkmcnt(0)
	v_mfma_f32_16x16x32_bf16 v[4:7], v[12:15], v[100:103], 0
	s_nop 4
	ds_read_b128 v[0:3], v141 offset:9216
	ds_read_b128 v[12:15], v141 offset:9280
	v_mfma_f32_16x16x32_bf16 v[88:91], v[16:19], v[8:11], v[4:7]
	s_waitcnt lgkmcnt(1)
	v_mfma_f32_16x16x32_bf16 v[0:3], v[0:3], v[100:103], 0
	s_nop 0
	v_mad_i64_i32 v[4:5], s[14:15], v22, s63, v[20:21]
	v_lshl_add_u64 v[4:5], v[114:115], 1, v[4:5]
	v_lshl_add_u64 v[16:17], v[4:5], 0, v[188:189]
	ds_read_b128 v[4:7], v141 offset:11520
	v_add_co_u32_e32 v22, vcc, 0x1000, v16
	v_lshl_add_u64 v[20:21], v[16:17], 0, s[24:25]
	s_nop 0
	v_addc_co_u32_e32 v23, vcc, 0, v17, vcc
	s_waitcnt lgkmcnt(1)
	v_mfma_f32_16x16x32_bf16 v[84:87], v[12:15], v[8:11], v[0:3]
	ds_read_b128 v[12:15], v141 offset:11584
	s_waitcnt lgkmcnt(1)
	v_mfma_f32_16x16x32_bf16 v[16:19], v[4:7], v[100:103], 0
	global_load_dwordx4 v[0:3], v[22:23], off offset:2048
	global_load_dwordx4 v[4:7], v[20:21], off offset:64
	s_waitcnt lgkmcnt(0)
	v_mfma_f32_16x16x32_bf16 v[80:83], v[12:15], v[8:11], v[16:19]
	ds_read_b128 v[12:15], v141 offset:13824
	s_nop 2
	ds_read_b128 v[16:19], v141 offset:13888
	ds_read_b128 v[20:23], v141 offset:16128
	ds_read_b128 v[24:27], v141 offset:16192
	s_waitcnt lgkmcnt(3)
	v_mfma_f32_16x16x32_bf16 v[12:15], v[12:15], v[100:103], 0
	s_waitcnt lgkmcnt(2)
	v_mfma_f32_16x16x32_bf16 v[76:79], v[16:19], v[8:11], v[12:15]
	ds_read_b128 v[16:19], v141 offset:18496
	s_nop 4
	ds_read_b128 v[12:15], v141 offset:18432
	s_waitcnt lgkmcnt(3)
	v_mfma_f32_16x16x32_bf16 v[20:23], v[20:23], v[100:103], 0
	s_waitcnt lgkmcnt(2)
	v_mfma_f32_16x16x32_bf16 v[72:75], v[24:27], v[8:11], v[20:23]
	s_waitcnt lgkmcnt(0)
	v_mfma_f32_16x16x32_bf16 v[12:15], v[12:15], v[100:103], 0
	s_nop 3
	ds_read_b128 v[20:23], v141 offset:20736
	v_mfma_f32_16x16x32_bf16 v[68:71], v[16:19], v[8:11], v[12:15]
	s_nop 2
	ds_read_b128 v[12:15], v141 offset:20800
	s_waitcnt lgkmcnt(1)
	v_mfma_f32_16x16x32_bf16 v[16:19], v[20:23], v[100:103], 0
	ds_read_b128 v[20:23], v141 offset:23040
	s_waitcnt lgkmcnt(1)
	v_mfma_f32_16x16x32_bf16 v[64:67], v[12:15], v[8:11], v[16:19]
	ds_read_b128 v[12:15], v141 offset:23104
	s_waitcnt lgkmcnt(1)
	v_mfma_f32_16x16x32_bf16 v[16:19], v[20:23], v[100:103], 0
	ds_read_b128 v[20:23], v141 offset:25344
	s_waitcnt lgkmcnt(1)
	v_mfma_f32_16x16x32_bf16 v[60:63], v[12:15], v[8:11], v[16:19]
	ds_read_b128 v[12:15], v141 offset:25408
	s_waitcnt lgkmcnt(1)
	v_mfma_f32_16x16x32_bf16 v[16:19], v[20:23], v[100:103], 0
	s_waitcnt lgkmcnt(0)
	v_mfma_f32_16x16x32_bf16 v[56:59], v[12:15], v[8:11], v[16:19]
	ds_read_b128 v[12:15], v141 offset:27648
	s_nop 4
	ds_read_b128 v[16:19], v141 offset:27712
	ds_read_b128 v[20:23], v141 offset:29952
	ds_read_b128 v[24:27], v141 offset:30016
	s_waitcnt lgkmcnt(3)
	v_mfma_f32_16x16x32_bf16 v[12:15], v[12:15], v[100:103], 0
	s_waitcnt lgkmcnt(2)
	v_mfma_f32_16x16x32_bf16 v[52:55], v[16:19], v[8:11], v[12:15]
	ds_read_b128 v[16:19], v141 offset:32320
	s_nop 4
	ds_read_b128 v[12:15], v141 offset:32256
	s_waitcnt lgkmcnt(3)
	v_mfma_f32_16x16x32_bf16 v[20:23], v[20:23], v[100:103], 0
	s_waitcnt lgkmcnt(2)
	v_mfma_f32_16x16x32_bf16 v[48:51], v[24:27], v[8:11], v[20:23]
	s_waitcnt lgkmcnt(0)
	v_mfma_f32_16x16x32_bf16 v[12:15], v[12:15], v[100:103], 0
	s_nop 3
	ds_read_b128 v[20:23], v141 offset:34560
	v_mfma_f32_16x16x32_bf16 v[44:47], v[16:19], v[8:11], v[12:15]
	s_nop 2
	ds_read_b128 v[12:15], v141 offset:34624
	s_waitcnt lgkmcnt(1)
	v_mfma_f32_16x16x32_bf16 v[16:19], v[20:23], v[100:103], 0
	ds_read_b128 v[20:23], v141 offset:36864
	s_waitcnt lgkmcnt(1)
	v_mfma_f32_16x16x32_bf16 v[40:43], v[12:15], v[8:11], v[16:19]
	ds_read_b128 v[12:15], v141 offset:36928
	s_waitcnt lgkmcnt(1)
	v_mfma_f32_16x16x32_bf16 v[16:19], v[20:23], v[100:103], 0
	ds_read_b128 v[20:23], v141 offset:39168
	s_waitcnt lgkmcnt(1)
	v_mfma_f32_16x16x32_bf16 v[36:39], v[12:15], v[8:11], v[16:19]
	ds_read_b128 v[12:15], v141 offset:39232
	s_waitcnt lgkmcnt(1)
	v_mfma_f32_16x16x32_bf16 v[16:19], v[20:23], v[100:103], 0
	s_waitcnt lgkmcnt(0)
	v_mfma_f32_16x16x32_bf16 v[32:35], v[12:15], v[8:11], v[16:19]
	ds_read_b128 v[12:15], v141 offset:41472
	s_nop 4
	ds_read_b128 v[16:19], v141 offset:41536
	s_waitcnt lgkmcnt(1)
	v_mfma_f32_16x16x32_bf16 v[12:15], v[12:15], v[100:103], 0
	ds_read_b128 v[150:153], v141 offset:50752
	s_waitcnt lgkmcnt(1)
	v_mfma_f32_16x16x32_bf16 v[28:31], v[16:19], v[8:11], v[12:15]
	ds_read_b128 v[16:19], v141 offset:43840
	s_nop 3
	ds_read_b128 v[12:15], v141 offset:43776
	s_waitcnt lgkmcnt(0)
	v_mfma_f32_16x16x32_bf16 v[12:15], v[12:15], v[100:103], 0
	v_mfma_f32_16x16x32_bf16 v[24:27], v[16:19], v[8:11], v[12:15]
	ds_read_b128 v[16:19], v141 offset:46144
	s_nop 5
	ds_read_b128 v[12:15], v141 offset:46080
	s_waitcnt lgkmcnt(0)
; __device__ void attn_mfma(const Params& p, int l, const bf16_t* proj, bf16_t* y0, LAS unsigned char* lds) {
;     ...
;             const float tq = (float)(tl + 128 - 4 * g);
;             float mx = sink;
; #pragma unroll
;             for (int kt = 0; kt < 24; ++kt)
; #pragma unroll
;                 for (int r = 0; r < 4; ++r) { const float x = (float)(kt * 16 + r) - tq; float sc = fmaf(sacc[kt][r], 0.125f, -slope * fabsf(x));
;                     bool valid = fabsf(x) <= 128.0f;
;                     if (edge) { const int kl = kt * 16 + 4 * g + r; valid = valid && (n == 0 ? kl >= 128 : kl < 256); }
;                     sc = valid ? sc : -1e30f; sacc[kt][r] = sc; mx = fmaxf(mx, sc); }
	v_mfma_f32_16x16x32_bf16 v[12:15], v[12:15], v[100:103], 0
	v_mfma_f32_16x16x32_bf16 v[20:23], v[16:19], v[8:11], v[12:15]
	ds_read_b128 v[16:19], v141 offset:48448
	s_nop 5
	ds_read_b128 v[12:15], v141 offset:48384
	s_waitcnt lgkmcnt(0)
	v_mfma_f32_16x16x32_bf16 v[12:15], v[12:15], v[100:103], 0
	v_mfma_f32_16x16x32_bf16 v[16:19], v[16:19], v[8:11], v[12:15]
	s_nop 6
	ds_read_b128 v[12:15], v141 offset:50688
	s_waitcnt lgkmcnt(0)
	v_mfma_f32_16x16x32_bf16 v[12:15], v[12:15], v[100:103], 0
	v_mfma_f32_16x16x32_bf16 v[12:15], v[150:153], v[8:11], v[12:15]
	ds_read_b128 v[150:153], v141 offset:52992
	s_waitcnt lgkmcnt(0)
	v_mfma_f32_16x16x32_bf16 v[100:103], v[150:153], v[100:103], 0
	ds_read_b128 v[150:153], v141 offset:53056
	s_waitcnt lgkmcnt(0)
	v_mfma_f32_16x16x32_bf16 v[8:11], v[150:153], v[8:11], v[100:103]
	s_nop 4
	v_add_u32_e32 v100, s12, v134
	v_cvt_f32_u32_e32 v101, v100
	v_cndmask_b32_e64 v119, 0, 1, s[4:5]
	v_sub_f32_e32 v100, 0, v101
	v_cmp_le_f32_e64 s[14:15], |v100|, s71
	v_cmp_nle_f32_e64 s[16:17], |v100|, s71
	s_and_b64 s[14:15], s[8:9], s[14:15]
	v_mul_f32_e64 v102, |v100|, -v147
	v_cndmask_b32_e64 v100, 0, 1, s[14:15]
	s_or_b64 vcc, s[8:9], s[16:17]
	v_cndmask_b32_e32 v100, v119, v100, vcc
	v_and_b32_e32 v100, 1, v100
	v_fmac_f32_e32 v102, 0x3e000000, v104
	v_cmp_eq_u32_e32 vcc, 1, v100
	s_nop 1
	v_cndmask_b32_e32 v100, v220, v102, vcc
	v_sub_f32_e32 v102, 1.0, v101
	v_cmp_le_f32_e64 s[14:15], |v102|, s71
	v_cmp_nle_f32_e64 s[16:17], |v102|, s71
	s_and_b64 s[14:15], s[8:9], s[14:15]
	v_mul_f32_e64 v103, |v102|, -v147
	v_cndmask_b32_e64 v102, 0, 1, s[14:15]
	s_or_b64 vcc, s[8:9], s[16:17]
	v_cndmask_b32_e32 v102, v119, v102, vcc
	v_and_b32_e32 v102, 1, v102
	v_fmac_f32_e32 v103, 0x3e000000, v105
	v_cmp_eq_u32_e32 vcc, 1, v102
	s_nop 1
	v_cndmask_b32_e32 v102, v220, v103, vcc
	v_sub_f32_e32 v103, 2.0, v101
	v_cmp_le_f32_e64 s[14:15], |v103|, s71
	v_cmp_nle_f32_e64 s[16:17], |v103|, s71
	s_and_b64 s[14:15], s[8:9], s[14:15]
	v_mul_f32_e64 v104, |v103|, -v147
	v_cndmask_b32_e64 v103, 0, 1, s[14:15]
	s_or_b64 vcc, s[8:9], s[16:17]
	v_cndmask_b32_e32 v103, v119, v103, vcc
	v_and_b32_e32 v103, 1, v103
	v_fmac_f32_e32 v104, 0x3e000000, v106
	v_cmp_eq_u32_e32 vcc, 1, v103
	s_waitcnt vmcnt(2)
	v_max3_f32 v105, v146, v100, v102
	v_cndmask_b32_e32 v103, v220, v104, vcc
	v_sub_f32_e32 v104, 0x40400000, v101
	v_cmp_le_f32_e64 s[14:15], |v104|, s71
	v_cmp_nle_f32_e64 s[16:17], |v104|, s71
	s_and_b64 s[14:15], s[8:9], s[14:15]
	v_mul_f32_e64 v106, |v104|, -v147
	v_cndmask_b32_e64 v104, 0, 1, s[14:15]
	s_or_b64 vcc, s[8:9], s[16:17]
	v_cndmask_b32_e32 v104, v119, v104, vcc
	v_and_b32_e32 v104, 1, v104
	v_fmac_f32_e32 v106, 0x3e000000, v107
	v_cmp_eq_u32_e32 vcc, 1, v104
	s_nop 1
	v_cndmask_b32_e32 v104, v220, v106, vcc
	v_sub_f32_e32 v106, 0x41800000, v101
	v_cmp_le_f32_e64 s[14:15], |v106|, s71
	v_mul_f32_e64 v107, |v106|, -v147
	v_cmp_nle_f32_e64 s[16:17], |v106|, s71
	s_and_b64 s[14:15], s[8:9], s[14:15]
	v_fmac_f32_e32 v107, 0x3e000000, v96
	v_cndmask_b32_e64 v96, 0, 1, s[14:15]
	s_or_b64 vcc, s[8:9], s[16:17]
	v_cndmask_b32_e32 v96, v119, v96, vcc
	v_and_b32_e32 v96, 1, v96
	v_sub_f32_e32 v106, 0x41880000, v101
	v_cmp_eq_u32_e32 vcc, 1, v96
	v_cmp_le_f32_e64 s[14:15], |v106|, s71
	v_cmp_nle_f32_e64 s[16:17], |v106|, s71
	v_cndmask_b32_e32 v96, v220, v107, vcc
	v_mul_f32_e64 v107, |v106|, -v147
	s_and_b64 s[14:15], s[8:9], s[14:15]
	v_fmac_f32_e32 v107, 0x3e000000, v97
	v_cndmask_b32_e64 v97, 0, 1, s[14:15]
	s_or_b64 vcc, s[8:9], s[16:17]
	v_cndmask_b32_e32 v97, v119, v97, vcc
	v_and_b32_e32 v97, 1, v97
	v_sub_f32_e32 v106, 0x41900000, v101
	v_cmp_eq_u32_e32 vcc, 1, v97
	v_cmp_le_f32_e64 s[14:15], |v106|, s71
	v_cmp_nle_f32_e64 s[16:17], |v106|, s71
	v_cndmask_b32_e32 v97, v220, v107, vcc
	v_mul_f32_e64 v107, |v106|, -v147
	s_and_b64 s[14:15], s[8:9], s[14:15]
	v_fmac_f32_e32 v107, 0x3e000000, v98
	v_cndmask_b32_e64 v98, 0, 1, s[14:15]
	s_or_b64 vcc, s[8:9], s[16:17]
	v_cndmask_b32_e32 v98, v119, v98, vcc
	v_and_b32_e32 v98, 1, v98
	v_sub_f32_e32 v106, 0x41980000, v101
	v_cmp_eq_u32_e32 vcc, 1, v98
	v_cmp_le_f32_e64 s[14:15], |v106|, s71
	v_cmp_nle_f32_e64 s[16:17], |v106|, s71
	v_cndmask_b32_e32 v98, v220, v107, vcc
	v_mul_f32_e64 v107, |v106|, -v147
	s_and_b64 s[14:15], s[8:9], s[14:15]
	v_fmac_f32_e32 v107, 0x3e000000, v99
	v_cndmask_b32_e64 v99, 0, 1, s[14:15]
	s_or_b64 vcc, s[8:9], s[16:17]
	v_cndmask_b32_e32 v99, v119, v99, vcc
	v_and_b32_e32 v99, 1, v99
	v_sub_f32_e32 v106, 0x42000000, v101
	v_cmp_eq_u32_e32 vcc, 1, v99
	v_cmp_le_f32_e64 s[14:15], |v106|, s71
	v_cmp_nle_f32_e64 s[16:17], |v106|, s71
	v_cndmask_b32_e32 v99, v220, v107, vcc
	v_mul_f32_e64 v107, |v106|, -v147
	s_and_b64 s[14:15], s[8:9], s[14:15]
	v_fmac_f32_e32 v107, 0x3e000000, v92
	v_cndmask_b32_e64 v92, 0, 1, s[14:15]
	s_or_b64 vcc, s[8:9], s[16:17]
	v_cndmask_b32_e32 v92, v119, v92, vcc
	v_and_b32_e32 v92, 1, v92
	v_sub_f32_e32 v106, 0x42040000, v101
	v_cmp_eq_u32_e32 vcc, 1, v92
	v_cmp_le_f32_e64 s[14:15], |v106|, s71
	v_cmp_nle_f32_e64 s[16:17], |v106|, s71
	v_cndmask_b32_e32 v92, v220, v107, vcc
	v_mul_f32_e64 v107, |v106|, -v147
	s_and_b64 s[14:15], s[8:9], s[14:15]
	v_fmac_f32_e32 v107, 0x3e000000, v93
	v_cndmask_b32_e64 v93, 0, 1, s[14:15]
	s_or_b64 vcc, s[8:9], s[16:17]
	v_cndmask_b32_e32 v93, v119, v93, vcc
	v_and_b32_e32 v93, 1, v93
	v_sub_f32_e32 v106, 0x42080000, v101
	v_cmp_eq_u32_e32 vcc, 1, v93
	v_cmp_le_f32_e64 s[14:15], |v106|, s71
	v_cmp_nle_f32_e64 s[16:17], |v106|, s71
	v_cndmask_b32_e32 v93, v220, v107, vcc
	v_mul_f32_e64 v107, |v106|, -v147
	s_and_b64 s[14:15], s[8:9], s[14:15]
	v_fmac_f32_e32 v107, 0x3e000000, v94
; __device__ void attn_mfma(const Params& p, int l, const bf16_t* proj, bf16_t* y0, LAS unsigned char* lds) {
;     ...
;             const float tq = (float)(tl + 128 - 4 * g);
;             float mx = sink;
; #pragma unroll
;             for (int kt = 0; kt < 24; ++kt)
; #pragma unroll
;                 for (int r = 0; r < 4; ++r) { const float x = (float)(kt * 16 + r) - tq; float sc = fmaf(sacc[kt][r], 0.125f, -slope * fabsf(x));
;                     bool valid = fabsf(x) <= 128.0f;
;                     if (edge) { const int kl = kt * 16 + 4 * g + r; valid = valid && (n == 0 ? kl >= 128 : kl < 256); }
;                     sc = valid ? sc : -1e30f; sacc[kt][r] = sc; mx = fmaxf(mx, sc); }
	v_cndmask_b32_e64 v94, 0, 1, s[14:15]
	s_or_b64 vcc, s[8:9], s[16:17]
	v_cndmask_b32_e32 v94, v119, v94, vcc
	v_and_b32_e32 v94, 1, v94
	v_sub_f32_e32 v106, 0x420c0000, v101
	v_cmp_eq_u32_e32 vcc, 1, v94
	v_cmp_le_f32_e64 s[14:15], |v106|, s71
	v_cmp_nle_f32_e64 s[16:17], |v106|, s71
	v_cndmask_b32_e32 v94, v220, v107, vcc
	v_mul_f32_e64 v107, |v106|, -v147
	s_and_b64 s[14:15], s[8:9], s[14:15]
	v_fmac_f32_e32 v107, 0x3e000000, v95
	v_cndmask_b32_e64 v95, 0, 1, s[14:15]
	s_or_b64 vcc, s[8:9], s[16:17]
	v_cndmask_b32_e32 v95, v119, v95, vcc
	v_and_b32_e32 v95, 1, v95
	v_sub_f32_e32 v106, 0x42400000, v101
	v_cmp_eq_u32_e32 vcc, 1, v95
	v_cmp_le_f32_e64 s[14:15], |v106|, s71
	v_cmp_nle_f32_e64 s[16:17], |v106|, s71
	v_cndmask_b32_e32 v95, v220, v107, vcc
	v_mul_f32_e64 v107, |v106|, -v147
	s_and_b64 s[14:15], s[8:9], s[14:15]
	v_fmac_f32_e32 v107, 0x3e000000, v88
	v_cndmask_b32_e64 v88, 0, 1, s[14:15]
	s_or_b64 vcc, s[8:9], s[16:17]
	v_cndmask_b32_e32 v88, v119, v88, vcc
	v_and_b32_e32 v88, 1, v88
	v_sub_f32_e32 v106, 0x42440000, v101
	v_cmp_eq_u32_e32 vcc, 1, v88
	v_cmp_le_f32_e64 s[14:15], |v106|, s71
	v_cmp_nle_f32_e64 s[16:17], |v106|, s71
	v_cndmask_b32_e32 v88, v220, v107, vcc
	v_mul_f32_e64 v107, |v106|, -v147
	s_and_b64 s[14:15], s[8:9], s[14:15]
	v_fmac_f32_e32 v107, 0x3e000000, v89
	v_cndmask_b32_e64 v89, 0, 1, s[14:15]
	s_or_b64 vcc, s[8:9], s[16:17]
	v_cndmask_b32_e32 v89, v119, v89, vcc
	v_and_b32_e32 v89, 1, v89
	v_sub_f32_e32 v106, 0x42480000, v101
	v_cmp_eq_u32_e32 vcc, 1, v89
	v_cmp_le_f32_e64 s[14:15], |v106|, s71
	v_cmp_nle_f32_e64 s[16:17], |v106|, s71
	v_cndmask_b32_e32 v89, v220, v107, vcc
	v_mul_f32_e64 v107, |v106|, -v147
	s_and_b64 s[14:15], s[8:9], s[14:15]
	v_fmac_f32_e32 v107, 0x3e000000, v90
	v_cndmask_b32_e64 v90, 0, 1, s[14:15]
	s_or_b64 vcc, s[8:9], s[16:17]
	v_cndmask_b32_e32 v90, v119, v90, vcc
	v_and_b32_e32 v90, 1, v90
	v_sub_f32_e32 v106, 0x424c0000, v101
	v_cmp_eq_u32_e32 vcc, 1, v90
	v_cmp_le_f32_e64 s[14:15], |v106|, s71
	v_cmp_nle_f32_e64 s[16:17], |v106|, s71
	v_cndmask_b32_e32 v90, v220, v107, vcc
	v_mul_f32_e64 v107, |v106|, -v147
	s_and_b64 s[14:15], s[8:9], s[14:15]
	v_fmac_f32_e32 v107, 0x3e000000, v91
	v_cndmask_b32_e64 v91, 0, 1, s[14:15]
	s_or_b64 vcc, s[8:9], s[16:17]
	v_cndmask_b32_e32 v91, v119, v91, vcc
	v_and_b32_e32 v91, 1, v91
	v_sub_f32_e32 v106, 0x42800000, v101
	v_cmp_eq_u32_e32 vcc, 1, v91
	v_cmp_le_f32_e64 s[14:15], |v106|, s71
	v_cmp_nle_f32_e64 s[16:17], |v106|, s71
	v_cndmask_b32_e32 v91, v220, v107, vcc
	v_mul_f32_e64 v107, |v106|, -v147
	s_and_b64 s[14:15], s[8:9], s[14:15]
	v_fmac_f32_e32 v107, 0x3e000000, v84
	v_cndmask_b32_e64 v84, 0, 1, s[14:15]
	s_or_b64 vcc, s[8:9], s[16:17]
	v_cndmask_b32_e32 v84, v119, v84, vcc
	v_and_b32_e32 v84, 1, v84
	v_sub_f32_e32 v106, 0x42820000, v101
	v_cmp_eq_u32_e32 vcc, 1, v84
	v_cmp_le_f32_e64 s[14:15], |v106|, s71
	v_cmp_nle_f32_e64 s[16:17], |v106|, s71
	v_cndmask_b32_e32 v84, v220, v107, vcc
	v_mul_f32_e64 v107, |v106|, -v147
	s_and_b64 s[14:15], s[8:9], s[14:15]
	v_fmac_f32_e32 v107, 0x3e000000, v85
	v_cndmask_b32_e64 v85, 0, 1, s[14:15]
	s_or_b64 vcc, s[8:9], s[16:17]
	v_cndmask_b32_e32 v85, v119, v85, vcc
	v_and_b32_e32 v85, 1, v85
	v_sub_f32_e32 v106, 0x42840000, v101
	v_cmp_eq_u32_e32 vcc, 1, v85
	v_cmp_le_f32_e64 s[14:15], |v106|, s71
	v_cmp_nle_f32_e64 s[16:17], |v106|, s71
	v_cndmask_b32_e32 v85, v220, v107, vcc
	v_mul_f32_e64 v107, |v106|, -v147
	s_and_b64 s[14:15], s[8:9], s[14:15]
	v_fmac_f32_e32 v107, 0x3e000000, v86
	v_cndmask_b32_e64 v86, 0, 1, s[14:15]
	s_or_b64 vcc, s[8:9], s[16:17]
	v_cndmask_b32_e32 v86, v119, v86, vcc
	v_and_b32_e32 v86, 1, v86
	v_sub_f32_e32 v106, 0x42860000, v101
	v_cmp_eq_u32_e32 vcc, 1, v86
	v_cmp_le_f32_e64 s[14:15], |v106|, s71
	v_cmp_nle_f32_e64 s[16:17], |v106|, s71
	v_cndmask_b32_e32 v86, v220, v107, vcc
	v_mul_f32_e64 v107, |v106|, -v147
	s_and_b64 s[14:15], s[8:9], s[14:15]
	v_fmac_f32_e32 v107, 0x3e000000, v87
	v_cndmask_b32_e64 v87, 0, 1, s[14:15]
	s_or_b64 vcc, s[8:9], s[16:17]
	v_cndmask_b32_e32 v87, v119, v87, vcc
	v_and_b32_e32 v87, 1, v87
	v_sub_f32_e32 v106, 0x42a00000, v101
	v_cmp_eq_u32_e32 vcc, 1, v87
	v_cmp_le_f32_e64 s[14:15], |v106|, s71
	v_cmp_nle_f32_e64 s[16:17], |v106|, s71
	v_cndmask_b32_e32 v87, v220, v107, vcc
	v_mul_f32_e64 v107, |v106|, -v147
	s_and_b64 s[14:15], s[8:9], s[14:15]
	v_fmac_f32_e32 v107, 0x3e000000, v80
	v_cndmask_b32_e64 v80, 0, 1, s[14:15]
	s_or_b64 vcc, s[8:9], s[16:17]
	v_cndmask_b32_e32 v80, v119, v80, vcc
	v_and_b32_e32 v80, 1, v80
	v_sub_f32_e32 v106, 0x42a20000, v101
	v_cmp_eq_u32_e32 vcc, 1, v80
	v_cmp_le_f32_e64 s[14:15], |v106|, s71
	v_cmp_nle_f32_e64 s[16:17], |v106|, s71
	v_cndmask_b32_e32 v80, v220, v107, vcc
	v_mul_f32_e64 v107, |v106|, -v147
	s_and_b64 s[14:15], s[8:9], s[14:15]
	v_fmac_f32_e32 v107, 0x3e000000, v81
	v_cndmask_b32_e64 v81, 0, 1, s[14:15]
	s_or_b64 vcc, s[8:9], s[16:17]
	v_cndmask_b32_e32 v81, v119, v81, vcc
	v_and_b32_e32 v81, 1, v81
	v_sub_f32_e32 v106, 0x42a40000, v101
	v_cmp_eq_u32_e32 vcc, 1, v81
	v_cmp_le_f32_e64 s[14:15], |v106|, s71
	v_cmp_nle_f32_e64 s[16:17], |v106|, s71
	v_cndmask_b32_e32 v81, v220, v107, vcc
	v_mul_f32_e64 v107, |v106|, -v147
	s_and_b64 s[14:15], s[8:9], s[14:15]
	v_fmac_f32_e32 v107, 0x3e000000, v82
	v_cndmask_b32_e64 v82, 0, 1, s[14:15]
	s_or_b64 vcc, s[8:9], s[16:17]
	v_cndmask_b32_e32 v82, v119, v82, vcc
	v_and_b32_e32 v82, 1, v82
	v_sub_f32_e32 v106, 0x42a60000, v101
	v_cmp_eq_u32_e32 vcc, 1, v82
	v_cmp_le_f32_e64 s[14:15], |v106|, s71
	v_cmp_nle_f32_e64 s[16:17], |v106|, s71
	v_cndmask_b32_e32 v82, v220, v107, vcc
	v_mul_f32_e64 v107, |v106|, -v147
	s_and_b64 s[14:15], s[8:9], s[14:15]
; __device__ void attn_mfma(const Params& p, int l, const bf16_t* proj, bf16_t* y0, LAS unsigned char* lds) {
;     ...
;             const float tq = (float)(tl + 128 - 4 * g);
;             float mx = sink;
; #pragma unroll
;             for (int kt = 0; kt < 24; ++kt)
; #pragma unroll
;                 for (int r = 0; r < 4; ++r) { const float x = (float)(kt * 16 + r) - tq; float sc = fmaf(sacc[kt][r], 0.125f, -slope * fabsf(x));
;                     bool valid = fabsf(x) <= 128.0f;
;                     if (edge) { const int kl = kt * 16 + 4 * g + r; valid = valid && (n == 0 ? kl >= 128 : kl < 256); }
;                     sc = valid ? sc : -1e30f; sacc[kt][r] = sc; mx = fmaxf(mx, sc); }
	v_fmac_f32_e32 v107, 0x3e000000, v83
	v_cndmask_b32_e64 v83, 0, 1, s[14:15]
	s_or_b64 vcc, s[8:9], s[16:17]
	v_cndmask_b32_e32 v83, v119, v83, vcc
	v_and_b32_e32 v83, 1, v83
	v_sub_f32_e32 v106, 0x42c00000, v101
	v_cmp_eq_u32_e32 vcc, 1, v83
	v_cmp_le_f32_e64 s[14:15], |v106|, s71
	v_cmp_nle_f32_e64 s[16:17], |v106|, s71
	v_cndmask_b32_e32 v83, v220, v107, vcc
	v_mul_f32_e64 v107, |v106|, -v147
	s_and_b64 s[14:15], s[8:9], s[14:15]
	v_fmac_f32_e32 v107, 0x3e000000, v76
	v_cndmask_b32_e64 v76, 0, 1, s[14:15]
	s_or_b64 vcc, s[8:9], s[16:17]
	v_cndmask_b32_e32 v76, v119, v76, vcc
	v_and_b32_e32 v76, 1, v76
	v_sub_f32_e32 v106, 0x42c20000, v101
	v_cmp_eq_u32_e32 vcc, 1, v76
	v_cmp_le_f32_e64 s[14:15], |v106|, s71
	v_cmp_nle_f32_e64 s[16:17], |v106|, s71
	v_cndmask_b32_e32 v76, v220, v107, vcc
	v_mul_f32_e64 v107, |v106|, -v147
	s_and_b64 s[14:15], s[8:9], s[14:15]
	v_fmac_f32_e32 v107, 0x3e000000, v77
	v_cndmask_b32_e64 v77, 0, 1, s[14:15]
	s_or_b64 vcc, s[8:9], s[16:17]
	v_cndmask_b32_e32 v77, v119, v77, vcc
	v_and_b32_e32 v77, 1, v77
	v_sub_f32_e32 v106, 0x42c40000, v101
	v_cmp_eq_u32_e32 vcc, 1, v77
	v_cmp_le_f32_e64 s[14:15], |v106|, s71
	v_cmp_nle_f32_e64 s[16:17], |v106|, s71
	v_cndmask_b32_e32 v77, v220, v107, vcc
	v_mul_f32_e64 v107, |v106|, -v147
	s_and_b64 s[14:15], s[8:9], s[14:15]
	v_fmac_f32_e32 v107, 0x3e000000, v78
	v_cndmask_b32_e64 v78, 0, 1, s[14:15]
	s_or_b64 vcc, s[8:9], s[16:17]
	v_cndmask_b32_e32 v78, v119, v78, vcc
	v_and_b32_e32 v78, 1, v78
	v_sub_f32_e32 v106, 0x42c60000, v101
	v_cmp_eq_u32_e32 vcc, 1, v78
	v_cmp_le_f32_e64 s[14:15], |v106|, s71
	v_cmp_nle_f32_e64 s[16:17], |v106|, s71
	v_cndmask_b32_e32 v78, v220, v107, vcc
	v_mul_f32_e64 v107, |v106|, -v147
	s_and_b64 s[14:15], s[8:9], s[14:15]
	v_fmac_f32_e32 v107, 0x3e000000, v79
	v_cndmask_b32_e64 v79, 0, 1, s[14:15]
	s_or_b64 vcc, s[8:9], s[16:17]
	v_cndmask_b32_e32 v79, v119, v79, vcc
	v_max3_f32 v105, v105, v103, v104
	v_and_b32_e32 v79, 1, v79
	v_sub_f32_e32 v106, 0x42e00000, v101
	v_max3_f32 v105, v105, v96, v97
	v_cmp_eq_u32_e32 vcc, 1, v79
	v_cmp_le_f32_e64 s[14:15], |v106|, s71
	v_max3_f32 v105, v105, v98, v99
	v_cndmask_b32_e32 v79, v220, v107, vcc
	v_mul_f32_e64 v107, |v106|, -v147
	v_cmp_nle_f32_e64 s[16:17], |v106|, s71
	s_and_b64 s[14:15], s[8:9], s[14:15]
	v_max3_f32 v105, v105, v92, v93
	v_fmac_f32_e32 v107, 0x3e000000, v72
	v_cndmask_b32_e64 v72, 0, 1, s[14:15]
	s_or_b64 vcc, s[8:9], s[16:17]
	v_max3_f32 v105, v105, v94, v95
	v_cndmask_b32_e32 v72, v119, v72, vcc
	v_max3_f32 v105, v105, v88, v89
	v_and_b32_e32 v72, 1, v72
	v_sub_f32_e32 v106, 0x42e20000, v101
	v_max3_f32 v105, v105, v90, v91
	v_cmp_eq_u32_e32 vcc, 1, v72
	v_cmp_le_f32_e64 s[14:15], |v106|, s71
	v_max3_f32 v105, v105, v84, v85
	v_cndmask_b32_e32 v72, v220, v107, vcc
	v_mul_f32_e64 v107, |v106|, -v147
	v_cmp_nle_f32_e64 s[16:17], |v106|, s71
	s_and_b64 s[14:15], s[8:9], s[14:15]
	v_max3_f32 v105, v105, v86, v87
	v_fmac_f32_e32 v107, 0x3e000000, v73
	v_cndmask_b32_e64 v73, 0, 1, s[14:15]
	s_or_b64 vcc, s[8:9], s[16:17]
	v_max3_f32 v105, v105, v80, v81
	v_cndmask_b32_e32 v73, v119, v73, vcc
	v_max3_f32 v105, v105, v82, v83
	v_and_b32_e32 v73, 1, v73
	v_max3_f32 v105, v105, v76, v77
	v_cmp_eq_u32_e32 vcc, 1, v73
	v_max3_f32 v105, v105, v78, v79
	s_nop 0
	v_cndmask_b32_e32 v73, v220, v107, vcc
	v_max3_f32 v106, v105, v72, v73
	v_sub_f32_e32 v105, 0x42e40000, v101
	v_cmp_le_f32_e64 s[14:15], |v105|, s71
	v_mul_f32_e64 v107, |v105|, -v147
	v_cmp_nle_f32_e64 s[16:17], |v105|, s71
	s_and_b64 s[14:15], s[8:9], s[14:15]
	v_fmac_f32_e32 v107, 0x3e000000, v74
	v_cndmask_b32_e64 v74, 0, 1, s[14:15]
	s_or_b64 vcc, s[8:9], s[16:17]
	v_cndmask_b32_e32 v74, v119, v74, vcc
	v_and_b32_e32 v74, 1, v74
	v_cmp_eq_u32_e32 vcc, 1, v74
	v_sub_f32_e32 v74, 0x42e60000, v101
	v_cmp_le_f32_e64 s[14:15], |v74|, s71
	v_cmp_nle_f32_e64 s[16:17], |v74|, s71
	s_and_b64 s[14:15], s[8:9], s[14:15]
	v_cndmask_b32_e32 v105, v220, v107, vcc
	v_mul_f32_e64 v107, |v74|, -v147
	v_cndmask_b32_e64 v74, 0, 1, s[14:15]
	s_or_b64 vcc, s[8:9], s[16:17]
	v_cndmask_b32_e32 v74, v119, v74, vcc
	v_and_b32_e32 v74, 1, v74
	v_fmac_f32_e32 v107, 0x3e000000, v75
	v_cmp_eq_u32_e32 vcc, 1, v74
	v_sub_f32_e32 v75, 0x43000000, v101
	v_cndmask_b32_e64 v119, 0, 1, s[6:7]
	v_cndmask_b32_e32 v107, v220, v107, vcc
	v_max3_f32 v74, v106, v105, v107
	v_mul_f32_e64 v106, |v75|, -v147
	v_fmac_f32_e32 v106, 0x3e000000, v68
	v_sub_f32_e32 v68, 0x43010000, v101
	v_cmp_le_f32_e64 vcc, |v75|, s71
	v_mul_f32_e64 v75, |v68|, -v147
	v_fmac_f32_e32 v75, 0x3e000000, v69
	v_cndmask_b32_e32 v106, v220, v106, vcc
	v_cmp_le_f32_e64 vcc, |v68|, s71
	v_sub_f32_e32 v69, 0x43020000, v101
	s_nop 0
	v_cndmask_b32_e32 v75, v220, v75, vcc
	v_max3_f32 v68, v74, v106, v75
	v_mul_f32_e64 v74, |v69|, -v147
	v_cmp_le_f32_e64 vcc, |v69|, s71
	v_sub_f32_e32 v69, 0x43030000, v101
	v_fmac_f32_e32 v74, 0x3e000000, v70
	v_mul_f32_e64 v70, |v69|, -v147
	v_cndmask_b32_e32 v74, v220, v74, vcc
	v_fmac_f32_e32 v70, 0x3e000000, v71
	v_cmp_le_f32_e64 vcc, |v69|, s71
	v_sub_f32_e32 v69, 0x43100000, v101
	s_nop 0
	v_cndmask_b32_e32 v71, v220, v70, vcc
	v_mul_f32_e64 v70, |v69|, -v147
	v_fmac_f32_e32 v70, 0x3e000000, v64
	v_sub_f32_e32 v64, 0x43110000, v101
	v_cmp_le_f32_e64 vcc, |v69|, s71
	v_mul_f32_e64 v69, |v64|, -v147
	v_fmac_f32_e32 v69, 0x3e000000, v65
	v_cndmask_b32_e32 v70, v220, v70, vcc
	v_cmp_le_f32_e64 vcc, |v64|, s71
	v_max3_f32 v68, v68, v74, v71
	v_sub_f32_e32 v65, 0x43120000, v101
	v_cndmask_b32_e32 v69, v220, v69, vcc
	v_max3_f32 v64, v68, v70, v69
	v_mul_f32_e64 v68, |v65|, -v147
	v_cmp_le_f32_e64 vcc, |v65|, s71
	v_sub_f32_e32 v65, 0x43130000, v101
	v_fmac_f32_e32 v68, 0x3e000000, v66
; __device__ void attn_mfma(const Params& p, int l, const bf16_t* proj, bf16_t* y0, LAS unsigned char* lds) {
;     ...
;             const float tq = (float)(tl + 128 - 4 * g);
;             float mx = sink;
; #pragma unroll
;             for (int kt = 0; kt < 24; ++kt)
; #pragma unroll
;                 for (int r = 0; r < 4; ++r) { const float x = (float)(kt * 16 + r) - tq; float sc = fmaf(sacc[kt][r], 0.125f, -slope * fabsf(x));
;                     bool valid = fabsf(x) <= 128.0f;
;                     if (edge) { const int kl = kt * 16 + 4 * g + r; valid = valid && (n == 0 ? kl >= 128 : kl < 256); }
;                     sc = valid ? sc : -1e30f; sacc[kt][r] = sc; mx = fmaxf(mx, sc); }
	v_mul_f32_e64 v66, |v65|, -v147
	v_cndmask_b32_e32 v68, v220, v68, vcc
	v_fmac_f32_e32 v66, 0x3e000000, v67
	v_cmp_le_f32_e64 vcc, |v65|, s71
	v_sub_f32_e32 v65, 0x43200000, v101
	s_nop 0
	v_cndmask_b32_e32 v67, v220, v66, vcc
	v_mul_f32_e64 v66, |v65|, -v147
	v_fmac_f32_e32 v66, 0x3e000000, v60
	v_sub_f32_e32 v60, 0x43210000, v101
	v_cmp_le_f32_e64 vcc, |v65|, s71
	v_mul_f32_e64 v65, |v60|, -v147
	v_fmac_f32_e32 v65, 0x3e000000, v61
	v_cndmask_b32_e32 v66, v220, v66, vcc
	v_cmp_le_f32_e64 vcc, |v60|, s71
	v_max3_f32 v64, v64, v68, v67
	v_sub_f32_e32 v61, 0x43220000, v101
	v_cndmask_b32_e32 v65, v220, v65, vcc
	v_max3_f32 v60, v64, v66, v65
	v_mul_f32_e64 v64, |v61|, -v147
	v_cmp_le_f32_e64 vcc, |v61|, s71
	v_sub_f32_e32 v61, 0x43230000, v101
	v_fmac_f32_e32 v64, 0x3e000000, v62
	v_mul_f32_e64 v62, |v61|, -v147
	v_cndmask_b32_e32 v64, v220, v64, vcc
	v_fmac_f32_e32 v62, 0x3e000000, v63
	v_cmp_le_f32_e64 vcc, |v61|, s71
	v_sub_f32_e32 v61, 0x43300000, v101
	s_nop 0
	v_cndmask_b32_e32 v63, v220, v62, vcc
	v_mul_f32_e64 v62, |v61|, -v147
	v_fmac_f32_e32 v62, 0x3e000000, v56
	v_sub_f32_e32 v56, 0x43310000, v101
	v_cmp_le_f32_e64 vcc, |v61|, s71
	v_mul_f32_e64 v61, |v56|, -v147
	v_fmac_f32_e32 v61, 0x3e000000, v57
	v_cndmask_b32_e32 v62, v220, v62, vcc
	v_cmp_le_f32_e64 vcc, |v56|, s71
	v_max3_f32 v60, v60, v64, v63
	v_sub_f32_e32 v57, 0x43320000, v101
	v_cndmask_b32_e32 v61, v220, v61, vcc
	v_max3_f32 v56, v60, v62, v61
	v_mul_f32_e64 v60, |v57|, -v147
	v_cmp_le_f32_e64 vcc, |v57|, s71
	v_sub_f32_e32 v57, 0x43330000, v101
	v_fmac_f32_e32 v60, 0x3e000000, v58
	v_mul_f32_e64 v58, |v57|, -v147
	v_cndmask_b32_e32 v60, v220, v60, vcc
	v_fmac_f32_e32 v58, 0x3e000000, v59
	v_cmp_le_f32_e64 vcc, |v57|, s71
	v_sub_f32_e32 v57, 0x43400000, v101
	s_nop 0
	v_cndmask_b32_e32 v59, v220, v58, vcc
	v_mul_f32_e64 v58, |v57|, -v147
	v_fmac_f32_e32 v58, 0x3e000000, v52
	v_sub_f32_e32 v52, 0x43410000, v101
	v_cmp_le_f32_e64 vcc, |v57|, s71
	v_mul_f32_e64 v57, |v52|, -v147
	v_fmac_f32_e32 v57, 0x3e000000, v53
	v_cndmask_b32_e32 v58, v220, v58, vcc
	v_cmp_le_f32_e64 vcc, |v52|, s71
	v_max3_f32 v56, v56, v60, v59
	v_sub_f32_e32 v53, 0x43420000, v101
	v_cndmask_b32_e32 v57, v220, v57, vcc
	v_max3_f32 v52, v56, v58, v57
	v_mul_f32_e64 v56, |v53|, -v147
	v_cmp_le_f32_e64 vcc, |v53|, s71
	v_sub_f32_e32 v53, 0x43430000, v101
	v_fmac_f32_e32 v56, 0x3e000000, v54
	v_mul_f32_e64 v54, |v53|, -v147
	v_cndmask_b32_e32 v56, v220, v56, vcc
	v_fmac_f32_e32 v54, 0x3e000000, v55
	v_cmp_le_f32_e64 vcc, |v53|, s71
	v_sub_f32_e32 v53, 0x43500000, v101
	s_nop 0
	v_cndmask_b32_e32 v55, v220, v54, vcc
	v_mul_f32_e64 v54, |v53|, -v147
	v_fmac_f32_e32 v54, 0x3e000000, v48
	v_sub_f32_e32 v48, 0x43510000, v101
	v_cmp_le_f32_e64 vcc, |v53|, s71
	v_mul_f32_e64 v53, |v48|, -v147
	v_fmac_f32_e32 v53, 0x3e000000, v49
	v_cndmask_b32_e32 v54, v220, v54, vcc
	v_cmp_le_f32_e64 vcc, |v48|, s71
	v_max3_f32 v52, v52, v56, v55
	v_sub_f32_e32 v49, 0x43520000, v101
	v_cndmask_b32_e32 v53, v220, v53, vcc
	v_max3_f32 v48, v52, v54, v53
	v_mul_f32_e64 v52, |v49|, -v147
	v_cmp_le_f32_e64 vcc, |v49|, s71
	v_sub_f32_e32 v49, 0x43530000, v101
	v_fmac_f32_e32 v52, 0x3e000000, v50
	v_mul_f32_e64 v50, |v49|, -v147
	v_cndmask_b32_e32 v52, v220, v52, vcc
	v_fmac_f32_e32 v50, 0x3e000000, v51
	v_cmp_le_f32_e64 vcc, |v49|, s71
	v_sub_f32_e32 v49, 0x43600000, v101
	s_nop 0
	v_cndmask_b32_e32 v51, v220, v50, vcc
	v_mul_f32_e64 v50, |v49|, -v147
	v_fmac_f32_e32 v50, 0x3e000000, v44
	v_sub_f32_e32 v44, 0x43610000, v101
	v_cmp_le_f32_e64 vcc, |v49|, s71
	v_mul_f32_e64 v49, |v44|, -v147
	v_fmac_f32_e32 v49, 0x3e000000, v45
	v_cndmask_b32_e32 v50, v220, v50, vcc
	v_cmp_le_f32_e64 vcc, |v44|, s71
	v_max3_f32 v48, v48, v52, v51
	v_sub_f32_e32 v45, 0x43620000, v101
	v_cndmask_b32_e32 v49, v220, v49, vcc
	v_max3_f32 v44, v48, v50, v49
	v_mul_f32_e64 v48, |v45|, -v147
	v_cmp_le_f32_e64 vcc, |v45|, s71
	v_sub_f32_e32 v45, 0x43630000, v101
	v_fmac_f32_e32 v48, 0x3e000000, v46
	v_mul_f32_e64 v46, |v45|, -v147
	v_cndmask_b32_e32 v48, v220, v48, vcc
	v_fmac_f32_e32 v46, 0x3e000000, v47
	v_cmp_le_f32_e64 vcc, |v45|, s71
	s_nop 1
	v_cndmask_b32_e32 v46, v220, v46, vcc
	v_max3_f32 v47, v44, v48, v46
	v_sub_f32_e32 v44, 0x43700000, v101
	v_mul_f32_e64 v45, |v44|, -v147
	v_fmac_f32_e32 v45, 0x3e000000, v40
	v_sub_f32_e32 v40, 0x43710000, v101
	v_cmp_le_f32_e64 vcc, |v44|, s71
	v_mul_f32_e64 v44, |v40|, -v147
	v_fmac_f32_e32 v44, 0x3e000000, v41
	v_cndmask_b32_e32 v45, v220, v45, vcc
	v_cmp_le_f32_e64 vcc, |v40|, s71
	v_sub_f32_e32 v40, 0x43720000, v101
	v_mul_f32_e64 v41, |v40|, -v147
	v_cndmask_b32_e32 v44, v220, v44, vcc
	v_cmp_le_f32_e64 vcc, |v40|, s71
	v_sub_f32_e32 v40, 0x43730000, v101
	v_fmac_f32_e32 v41, 0x3e000000, v42
	v_mul_f32_e64 v42, |v40|, -v147
	v_cndmask_b32_e32 v41, v220, v41, vcc
	v_fmac_f32_e32 v42, 0x3e000000, v43
	v_cmp_le_f32_e64 vcc, |v40|, s71
	v_sub_f32_e32 v43, 0x43800000, v101
	v_max3_f32 v47, v47, v45, v44
	v_cndmask_b32_e32 v40, v220, v42, vcc
	v_cmp_le_f32_e64 s[14:15], |v43|, s71
	v_max3_f32 v42, v47, v41, v40
	v_mul_f32_e64 v47, |v43|, -v147
	v_cmp_nle_f32_e64 s[16:17], |v43|, s71
	s_and_b64 s[14:15], s[8:9], s[14:15]
	v_fmac_f32_e32 v47, 0x3e000000, v36
	v_cndmask_b32_e64 v36, 0, 1, s[14:15]
	s_or_b64 vcc, s[8:9], s[16:17]
	v_cndmask_b32_e32 v36, v119, v36, vcc
	v_and_b32_e32 v36, 1, v36
	v_sub_f32_e32 v43, 0x43808000, v101
	v_cmp_eq_u32_e32 vcc, 1, v36
	v_cmp_le_f32_e64 s[14:15], |v43|, s71
	v_cmp_nle_f32_e64 s[16:17], |v43|, s71
	v_cndmask_b32_e32 v36, v220, v47, vcc
	v_mul_f32_e64 v47, |v43|, -v147
	s_and_b64 s[14:15], s[8:9], s[14:15]
	v_fmac_f32_e32 v47, 0x3e000000, v37
	v_cndmask_b32_e64 v37, 0, 1, s[14:15]
; __device__ void attn_mfma(const Params& p, int l, const bf16_t* proj, bf16_t* y0, LAS unsigned char* lds) {
;     ...
;             const float tq = (float)(tl + 128 - 4 * g);
;             float mx = sink;
; #pragma unroll
;             for (int kt = 0; kt < 24; ++kt)
; #pragma unroll
;                 for (int r = 0; r < 4; ++r) { const float x = (float)(kt * 16 + r) - tq; float sc = fmaf(sacc[kt][r], 0.125f, -slope * fabsf(x));
;                     bool valid = fabsf(x) <= 128.0f;
;                     if (edge) { const int kl = kt * 16 + 4 * g + r; valid = valid && (n == 0 ? kl >= 128 : kl < 256); }
;                     sc = valid ? sc : -1e30f; sacc[kt][r] = sc; mx = fmaxf(mx, sc); }
	s_or_b64 vcc, s[8:9], s[16:17]
	v_cndmask_b32_e32 v37, v119, v37, vcc
	v_and_b32_e32 v37, 1, v37
	v_sub_f32_e32 v43, 0x43810000, v101
	v_cmp_eq_u32_e32 vcc, 1, v37
	v_cmp_le_f32_e64 s[14:15], |v43|, s71
	v_cmp_nle_f32_e64 s[16:17], |v43|, s71
	v_cndmask_b32_e32 v37, v220, v47, vcc
	v_mul_f32_e64 v47, |v43|, -v147
	s_and_b64 s[14:15], s[8:9], s[14:15]
	v_fmac_f32_e32 v47, 0x3e000000, v38
	v_cndmask_b32_e64 v38, 0, 1, s[14:15]
	s_or_b64 vcc, s[8:9], s[16:17]
	v_cndmask_b32_e32 v38, v119, v38, vcc
	v_and_b32_e32 v38, 1, v38
	v_sub_f32_e32 v43, 0x43818000, v101
	v_cmp_eq_u32_e32 vcc, 1, v38
	v_cmp_le_f32_e64 s[14:15], |v43|, s71
	v_cmp_nle_f32_e64 s[16:17], |v43|, s71
	v_cndmask_b32_e32 v38, v220, v47, vcc
	v_mul_f32_e64 v47, |v43|, -v147
	s_and_b64 s[14:15], s[8:9], s[14:15]
	v_fmac_f32_e32 v47, 0x3e000000, v39
	v_cndmask_b32_e64 v39, 0, 1, s[14:15]
	s_or_b64 vcc, s[8:9], s[16:17]
	v_cndmask_b32_e32 v39, v119, v39, vcc
	v_and_b32_e32 v39, 1, v39
	v_sub_f32_e32 v43, 0x43880000, v101
	v_cmp_eq_u32_e32 vcc, 1, v39
	v_cmp_le_f32_e64 s[14:15], |v43|, s71
	v_cmp_nle_f32_e64 s[16:17], |v43|, s71
	v_cndmask_b32_e32 v39, v220, v47, vcc
	v_mul_f32_e64 v47, |v43|, -v147
	s_and_b64 s[14:15], s[8:9], s[14:15]
	v_fmac_f32_e32 v47, 0x3e000000, v32
	v_cndmask_b32_e64 v32, 0, 1, s[14:15]
	s_or_b64 vcc, s[8:9], s[16:17]
	v_cndmask_b32_e32 v32, v119, v32, vcc
	v_and_b32_e32 v32, 1, v32
	v_sub_f32_e32 v43, 0x43888000, v101
	v_cmp_eq_u32_e32 vcc, 1, v32
	v_cmp_le_f32_e64 s[14:15], |v43|, s71
	v_cmp_nle_f32_e64 s[16:17], |v43|, s71
	v_cndmask_b32_e32 v32, v220, v47, vcc
	v_mul_f32_e64 v47, |v43|, -v147
	s_and_b64 s[14:15], s[8:9], s[14:15]
	v_fmac_f32_e32 v47, 0x3e000000, v33
	v_cndmask_b32_e64 v33, 0, 1, s[14:15]
	s_or_b64 vcc, s[8:9], s[16:17]
	v_cndmask_b32_e32 v33, v119, v33, vcc
	v_and_b32_e32 v33, 1, v33
	v_sub_f32_e32 v43, 0x43890000, v101
	v_cmp_eq_u32_e32 vcc, 1, v33
	v_cmp_le_f32_e64 s[14:15], |v43|, s71
	v_cmp_nle_f32_e64 s[16:17], |v43|, s71
	v_cndmask_b32_e32 v33, v220, v47, vcc
	v_mul_f32_e64 v47, |v43|, -v147
	s_and_b64 s[14:15], s[8:9], s[14:15]
	v_fmac_f32_e32 v47, 0x3e000000, v34
	v_cndmask_b32_e64 v34, 0, 1, s[14:15]
	s_or_b64 vcc, s[8:9], s[16:17]
	v_cndmask_b32_e32 v34, v119, v34, vcc
	v_and_b32_e32 v34, 1, v34
	v_sub_f32_e32 v43, 0x43898000, v101
	v_cmp_eq_u32_e32 vcc, 1, v34
	v_cmp_le_f32_e64 s[14:15], |v43|, s71
	v_cmp_nle_f32_e64 s[16:17], |v43|, s71
	v_cndmask_b32_e32 v34, v220, v47, vcc
	v_mul_f32_e64 v47, |v43|, -v147
	s_and_b64 s[14:15], s[8:9], s[14:15]
	v_fmac_f32_e32 v47, 0x3e000000, v35
	v_cndmask_b32_e64 v35, 0, 1, s[14:15]
	s_or_b64 vcc, s[8:9], s[16:17]
	v_cndmask_b32_e32 v35, v119, v35, vcc
	v_and_b32_e32 v35, 1, v35
	v_sub_f32_e32 v43, 0x43900000, v101
	v_cmp_eq_u32_e32 vcc, 1, v35
	v_cmp_le_f32_e64 s[14:15], |v43|, s71
	v_cmp_nle_f32_e64 s[16:17], |v43|, s71
	v_cndmask_b32_e32 v35, v220, v47, vcc
	v_mul_f32_e64 v47, |v43|, -v147
	s_and_b64 s[14:15], s[8:9], s[14:15]
	v_fmac_f32_e32 v47, 0x3e000000, v28
	v_cndmask_b32_e64 v28, 0, 1, s[14:15]
	s_or_b64 vcc, s[8:9], s[16:17]
	v_cndmask_b32_e32 v28, v119, v28, vcc
	v_and_b32_e32 v28, 1, v28
	v_sub_f32_e32 v43, 0x43908000, v101
	v_cmp_eq_u32_e32 vcc, 1, v28
	v_cmp_le_f32_e64 s[14:15], |v43|, s71
	v_cmp_nle_f32_e64 s[16:17], |v43|, s71
	v_cndmask_b32_e32 v28, v220, v47, vcc
	v_mul_f32_e64 v47, |v43|, -v147
	s_and_b64 s[14:15], s[8:9], s[14:15]
	v_fmac_f32_e32 v47, 0x3e000000, v29
	v_cndmask_b32_e64 v29, 0, 1, s[14:15]
	s_or_b64 vcc, s[8:9], s[16:17]
	v_cndmask_b32_e32 v29, v119, v29, vcc
	v_and_b32_e32 v29, 1, v29
	v_sub_f32_e32 v43, 0x43910000, v101
	v_cmp_eq_u32_e32 vcc, 1, v29
	v_cmp_le_f32_e64 s[14:15], |v43|, s71
	v_cmp_nle_f32_e64 s[16:17], |v43|, s71
	v_cndmask_b32_e32 v29, v220, v47, vcc
	v_mul_f32_e64 v47, |v43|, -v147
	s_and_b64 s[14:15], s[8:9], s[14:15]
	v_fmac_f32_e32 v47, 0x3e000000, v30
	v_cndmask_b32_e64 v30, 0, 1, s[14:15]
	s_or_b64 vcc, s[8:9], s[16:17]
	v_cndmask_b32_e32 v30, v119, v30, vcc
	v_and_b32_e32 v30, 1, v30
	v_sub_f32_e32 v43, 0x43918000, v101
	v_cmp_eq_u32_e32 vcc, 1, v30
	v_cmp_le_f32_e64 s[14:15], |v43|, s71
	v_cmp_nle_f32_e64 s[16:17], |v43|, s71
	v_cndmask_b32_e32 v30, v220, v47, vcc
	v_mul_f32_e64 v47, |v43|, -v147
	s_and_b64 s[14:15], s[8:9], s[14:15]
	v_fmac_f32_e32 v47, 0x3e000000, v31
	v_cndmask_b32_e64 v31, 0, 1, s[14:15]
	s_or_b64 vcc, s[8:9], s[16:17]
	v_cndmask_b32_e32 v31, v119, v31, vcc
	v_and_b32_e32 v31, 1, v31
	v_sub_f32_e32 v43, 0x43980000, v101
	v_cmp_eq_u32_e32 vcc, 1, v31
	v_cmp_le_f32_e64 s[14:15], |v43|, s71
	v_cmp_nle_f32_e64 s[16:17], |v43|, s71
	v_cndmask_b32_e32 v31, v220, v47, vcc
	v_mul_f32_e64 v47, |v43|, -v147
	s_and_b64 s[14:15], s[8:9], s[14:15]
	v_fmac_f32_e32 v47, 0x3e000000, v24
	v_cndmask_b32_e64 v24, 0, 1, s[14:15]
	s_or_b64 vcc, s[8:9], s[16:17]
	v_cndmask_b32_e32 v24, v119, v24, vcc
	v_and_b32_e32 v24, 1, v24
	v_sub_f32_e32 v43, 0x43988000, v101
	v_cmp_eq_u32_e32 vcc, 1, v24
	v_cmp_le_f32_e64 s[14:15], |v43|, s71
	v_cmp_nle_f32_e64 s[16:17], |v43|, s71
	v_cndmask_b32_e32 v24, v220, v47, vcc
	v_mul_f32_e64 v47, |v43|, -v147
	s_and_b64 s[14:15], s[8:9], s[14:15]
	v_fmac_f32_e32 v47, 0x3e000000, v25
	v_cndmask_b32_e64 v25, 0, 1, s[14:15]
	s_or_b64 vcc, s[8:9], s[16:17]
	v_cndmask_b32_e32 v25, v119, v25, vcc
	v_and_b32_e32 v25, 1, v25
	v_sub_f32_e32 v43, 0x43990000, v101
	v_cmp_eq_u32_e32 vcc, 1, v25
	v_cmp_le_f32_e64 s[14:15], |v43|, s71
	v_cmp_nle_f32_e64 s[16:17], |v43|, s71
	v_cndmask_b32_e32 v25, v220, v47, vcc
	v_mul_f32_e64 v47, |v43|, -v147
	s_and_b64 s[14:15], s[8:9], s[14:15]
	v_fmac_f32_e32 v47, 0x3e000000, v26
	v_cndmask_b32_e64 v26, 0, 1, s[14:15]
	s_or_b64 vcc, s[8:9], s[16:17]
; __device__ void attn_mfma(const Params& p, int l, const bf16_t* proj, bf16_t* y0, LAS unsigned char* lds) {
;     ...
;             const float tq = (float)(tl + 128 - 4 * g);
;             float mx = sink;
; #pragma unroll
;             for (int kt = 0; kt < 24; ++kt)
; #pragma unroll
;                 for (int r = 0; r < 4; ++r) { const float x = (float)(kt * 16 + r) - tq; float sc = fmaf(sacc[kt][r], 0.125f, -slope * fabsf(x));
;                     bool valid = fabsf(x) <= 128.0f;
;                     if (edge) { const int kl = kt * 16 + 4 * g + r; valid = valid && (n == 0 ? kl >= 128 : kl < 256); }
;                     sc = valid ? sc : -1e30f; sacc[kt][r] = sc; mx = fmaxf(mx, sc); }
	v_cndmask_b32_e32 v26, v119, v26, vcc
	v_and_b32_e32 v26, 1, v26
	v_sub_f32_e32 v43, 0x43998000, v101
	v_cmp_eq_u32_e32 vcc, 1, v26
	v_cmp_le_f32_e64 s[14:15], |v43|, s71
	v_cmp_nle_f32_e64 s[16:17], |v43|, s71
	v_cndmask_b32_e32 v26, v220, v47, vcc
	v_mul_f32_e64 v47, |v43|, -v147
	s_and_b64 s[14:15], s[8:9], s[14:15]
	v_fmac_f32_e32 v47, 0x3e000000, v27
	v_cndmask_b32_e64 v27, 0, 1, s[14:15]
	s_or_b64 vcc, s[8:9], s[16:17]
	v_cndmask_b32_e32 v27, v119, v27, vcc
	v_and_b32_e32 v27, 1, v27
	v_sub_f32_e32 v43, 0x43a00000, v101
	v_cmp_eq_u32_e32 vcc, 1, v27
	v_cmp_le_f32_e64 s[14:15], |v43|, s71
	v_cmp_nle_f32_e64 s[16:17], |v43|, s71
	v_cndmask_b32_e32 v27, v220, v47, vcc
	v_mul_f32_e64 v47, |v43|, -v147
	s_and_b64 s[14:15], s[8:9], s[14:15]
	v_fmac_f32_e32 v47, 0x3e000000, v20
	v_cndmask_b32_e64 v20, 0, 1, s[14:15]
	s_or_b64 vcc, s[8:9], s[16:17]
	v_cndmask_b32_e32 v20, v119, v20, vcc
	v_and_b32_e32 v20, 1, v20
	v_sub_f32_e32 v43, 0x43a08000, v101
	v_cmp_eq_u32_e32 vcc, 1, v20
	v_cmp_le_f32_e64 s[14:15], |v43|, s71
	v_cmp_nle_f32_e64 s[16:17], |v43|, s71
	v_cndmask_b32_e32 v20, v220, v47, vcc
	v_mul_f32_e64 v47, |v43|, -v147
	s_and_b64 s[14:15], s[8:9], s[14:15]
	v_fmac_f32_e32 v47, 0x3e000000, v21
	v_cndmask_b32_e64 v21, 0, 1, s[14:15]
	s_or_b64 vcc, s[8:9], s[16:17]
	v_cndmask_b32_e32 v21, v119, v21, vcc
	v_and_b32_e32 v21, 1, v21
	v_sub_f32_e32 v43, 0x43a10000, v101
	v_cmp_eq_u32_e32 vcc, 1, v21
	v_cmp_le_f32_e64 s[14:15], |v43|, s71
	v_cmp_nle_f32_e64 s[16:17], |v43|, s71
	v_cndmask_b32_e32 v21, v220, v47, vcc
	v_mul_f32_e64 v47, |v43|, -v147
	s_and_b64 s[14:15], s[8:9], s[14:15]
	v_fmac_f32_e32 v47, 0x3e000000, v22
	v_cndmask_b32_e64 v22, 0, 1, s[14:15]
	s_or_b64 vcc, s[8:9], s[16:17]
	v_cndmask_b32_e32 v22, v119, v22, vcc
	v_and_b32_e32 v22, 1, v22
	v_sub_f32_e32 v43, 0x43a18000, v101
	v_cmp_eq_u32_e32 vcc, 1, v22
	v_cmp_le_f32_e64 s[14:15], |v43|, s71
	v_cmp_nle_f32_e64 s[16:17], |v43|, s71
	v_cndmask_b32_e32 v22, v220, v47, vcc
	v_mul_f32_e64 v47, |v43|, -v147
	s_and_b64 s[14:15], s[8:9], s[14:15]
	v_fmac_f32_e32 v47, 0x3e000000, v23
	v_cndmask_b32_e64 v23, 0, 1, s[14:15]
	s_or_b64 vcc, s[8:9], s[16:17]
	v_cndmask_b32_e32 v23, v119, v23, vcc
	v_and_b32_e32 v23, 1, v23
	v_sub_f32_e32 v43, 0x43a80000, v101
	v_cmp_eq_u32_e32 vcc, 1, v23
	v_cmp_le_f32_e64 s[14:15], |v43|, s71
	v_cmp_nle_f32_e64 s[16:17], |v43|, s71
	v_cndmask_b32_e32 v23, v220, v47, vcc
	v_mul_f32_e64 v47, |v43|, -v147
	s_and_b64 s[14:15], s[8:9], s[14:15]
	v_fmac_f32_e32 v47, 0x3e000000, v16
	v_cndmask_b32_e64 v16, 0, 1, s[14:15]
	s_or_b64 vcc, s[8:9], s[16:17]
	v_cndmask_b32_e32 v16, v119, v16, vcc
	v_and_b32_e32 v16, 1, v16
	v_sub_f32_e32 v43, 0x43a88000, v101
	v_cmp_eq_u32_e32 vcc, 1, v16
	v_cmp_le_f32_e64 s[14:15], |v43|, s71
	v_cmp_nle_f32_e64 s[16:17], |v43|, s71
	v_cndmask_b32_e32 v16, v220, v47, vcc
	v_mul_f32_e64 v47, |v43|, -v147
	s_and_b64 s[14:15], s[8:9], s[14:15]
	v_fmac_f32_e32 v47, 0x3e000000, v17
	v_cndmask_b32_e64 v17, 0, 1, s[14:15]
	s_or_b64 vcc, s[8:9], s[16:17]
	v_cndmask_b32_e32 v17, v119, v17, vcc
	v_and_b32_e32 v17, 1, v17
	v_sub_f32_e32 v43, 0x43a90000, v101
	v_cmp_eq_u32_e32 vcc, 1, v17
	v_cmp_le_f32_e64 s[14:15], |v43|, s71
	v_cmp_nle_f32_e64 s[16:17], |v43|, s71
	v_cndmask_b32_e32 v17, v220, v47, vcc
	v_mul_f32_e64 v47, |v43|, -v147
	s_and_b64 s[14:15], s[8:9], s[14:15]
	v_fmac_f32_e32 v47, 0x3e000000, v18
	v_cndmask_b32_e64 v18, 0, 1, s[14:15]
	s_or_b64 vcc, s[8:9], s[16:17]
	v_cndmask_b32_e32 v18, v119, v18, vcc
	v_and_b32_e32 v18, 1, v18
	v_sub_f32_e32 v43, 0x43a98000, v101
	v_cmp_eq_u32_e32 vcc, 1, v18
	v_cmp_le_f32_e64 s[14:15], |v43|, s71
	v_cmp_nle_f32_e64 s[16:17], |v43|, s71
	v_cndmask_b32_e32 v18, v220, v47, vcc
	v_mul_f32_e64 v47, |v43|, -v147
	s_and_b64 s[14:15], s[8:9], s[14:15]
	v_fmac_f32_e32 v47, 0x3e000000, v19
	v_cndmask_b32_e64 v19, 0, 1, s[14:15]
	s_or_b64 vcc, s[8:9], s[16:17]
	v_cndmask_b32_e32 v19, v119, v19, vcc
	v_and_b32_e32 v19, 1, v19
	v_sub_f32_e32 v43, 0x43b00000, v101
	v_cmp_eq_u32_e32 vcc, 1, v19
	v_cmp_le_f32_e64 s[14:15], |v43|, s71
	v_cmp_nle_f32_e64 s[16:17], |v43|, s71
	v_cndmask_b32_e32 v19, v220, v47, vcc
	v_mul_f32_e64 v47, |v43|, -v147
	s_and_b64 s[14:15], s[8:9], s[14:15]
	v_fmac_f32_e32 v47, 0x3e000000, v12
	v_cndmask_b32_e64 v12, 0, 1, s[14:15]
	s_or_b64 vcc, s[8:9], s[16:17]
	v_cndmask_b32_e32 v12, v119, v12, vcc
	v_and_b32_e32 v12, 1, v12
	v_sub_f32_e32 v43, 0x43b08000, v101
	v_cmp_eq_u32_e32 vcc, 1, v12
	v_cmp_le_f32_e64 s[14:15], |v43|, s71
	v_cmp_nle_f32_e64 s[16:17], |v43|, s71
	v_cndmask_b32_e32 v12, v220, v47, vcc
	v_mul_f32_e64 v47, |v43|, -v147
	s_and_b64 s[14:15], s[8:9], s[14:15]
	v_fmac_f32_e32 v47, 0x3e000000, v13
	v_cndmask_b32_e64 v13, 0, 1, s[14:15]
	s_or_b64 vcc, s[8:9], s[16:17]
	v_cndmask_b32_e32 v13, v119, v13, vcc
	v_max3_f32 v42, v42, v36, v37
	v_and_b32_e32 v13, 1, v13
	v_sub_f32_e32 v43, 0x43b10000, v101
	v_max3_f32 v42, v42, v38, v39
	v_cmp_eq_u32_e32 vcc, 1, v13
	v_cmp_le_f32_e64 s[14:15], |v43|, s71
	v_max3_f32 v42, v42, v32, v33
	v_cndmask_b32_e32 v13, v220, v47, vcc
	v_mul_f32_e64 v47, |v43|, -v147
	v_cmp_nle_f32_e64 s[16:17], |v43|, s71
	s_and_b64 s[14:15], s[8:9], s[14:15]
	v_max3_f32 v42, v42, v34, v35
	v_fmac_f32_e32 v47, 0x3e000000, v14
	v_cndmask_b32_e64 v14, 0, 1, s[14:15]
	s_or_b64 vcc, s[8:9], s[16:17]
	v_max3_f32 v42, v42, v28, v29
	v_cndmask_b32_e32 v14, v119, v14, vcc
	v_max3_f32 v42, v42, v30, v31
	v_and_b32_e32 v14, 1, v14
	v_sub_f32_e32 v43, 0x43b18000, v101
	v_max3_f32 v42, v42, v24, v25
	v_cmp_eq_u32_e32 vcc, 1, v14
	v_cmp_le_f32_e64 s[14:15], |v43|, s71
	v_max3_f32 v42, v42, v26, v27
	v_cndmask_b32_e32 v14, v220, v47, vcc
	v_mul_f32_e64 v47, |v43|, -v147
; __device__ void attn_mfma(const Params& p, int l, const bf16_t* proj, bf16_t* y0, LAS unsigned char* lds) {
;     ...
;             mx = fmaxf(mx, __shfl_xor(mx, 16)); mx = fmaxf(mx, __shfl_xor(mx, 32));
;             float sum = 0.f; const float mxl = mx * 1.44269504f;
; #pragma unroll
;             for (int kt = 0; kt < 24; ++kt)
; #pragma unroll
;                 for (int r = 0; r < 4; ++r) { const float pr = exp2f(fmaf(sacc[kt][r], 1.44269504f, -mxl)); sacc[kt][r] = pr; sum += pr; }
	v_cmp_nle_f32_e64 s[16:17], |v43|, s71
	s_and_b64 s[14:15], s[8:9], s[14:15]
	v_max3_f32 v42, v42, v20, v21
	v_fmac_f32_e32 v47, 0x3e000000, v15
	v_cndmask_b32_e64 v15, 0, 1, s[14:15]
	s_or_b64 vcc, s[8:9], s[16:17]
	v_max3_f32 v42, v42, v22, v23
	v_cndmask_b32_e32 v15, v119, v15, vcc
	v_max3_f32 v42, v42, v16, v17
	v_and_b32_e32 v15, 1, v15
	v_max3_f32 v42, v42, v18, v19
	v_cmp_eq_u32_e32 vcc, 1, v15
	v_max3_f32 v42, v42, v12, v13
	s_nop 0
	v_cndmask_b32_e32 v15, v220, v47, vcc
	v_max3_f32 v47, v42, v14, v15
	v_sub_f32_e32 v42, 0x43b80000, v101
	v_cmp_le_f32_e64 s[14:15], |v42|, s71
	v_mul_f32_e64 v43, |v42|, -v147
	v_cmp_nle_f32_e64 s[16:17], |v42|, s71
	s_and_b64 s[14:15], s[8:9], s[14:15]
	v_fmac_f32_e32 v43, 0x3e000000, v8
	v_cndmask_b32_e64 v8, 0, 1, s[14:15]
	s_or_b64 vcc, s[8:9], s[16:17]
	v_cndmask_b32_e32 v8, v119, v8, vcc
	v_and_b32_e32 v8, 1, v8
	v_cmp_eq_u32_e32 vcc, 1, v8
	v_sub_f32_e32 v8, 0x43b88000, v101
	v_cmp_le_f32_e64 s[14:15], |v8|, s71
	v_cmp_nle_f32_e64 s[16:17], |v8|, s71
	s_and_b64 s[14:15], s[8:9], s[14:15]
	v_cndmask_b32_e32 v42, v220, v43, vcc
	v_mul_f32_e64 v43, |v8|, -v147
	v_cndmask_b32_e64 v8, 0, 1, s[14:15]
	s_or_b64 vcc, s[8:9], s[16:17]
	v_cndmask_b32_e32 v8, v119, v8, vcc
	v_fmac_f32_e32 v43, 0x3e000000, v9
	v_and_b32_e32 v8, 1, v8
	v_sub_f32_e32 v9, 0x43b90000, v101
	v_cmp_eq_u32_e32 vcc, 1, v8
	v_cmp_le_f32_e64 s[14:15], |v9|, s71
	v_cmp_nle_f32_e64 s[16:17], |v9|, s71
	v_cndmask_b32_e32 v43, v220, v43, vcc
	s_and_b64 s[14:15], s[8:9], s[14:15]
	v_max3_f32 v8, v47, v42, v43
	v_mul_f32_e64 v47, |v9|, -v147
	v_cndmask_b32_e64 v9, 0, 1, s[14:15]
	s_or_b64 vcc, s[8:9], s[16:17]
	v_cndmask_b32_e32 v9, v119, v9, vcc
	v_and_b32_e32 v9, 1, v9
	v_cmp_eq_u32_e32 vcc, 1, v9
	v_sub_f32_e32 v9, 0x43b98000, v101
	v_cmp_le_f32_e64 s[14:15], |v9|, s71
	v_fmac_f32_e32 v47, 0x3e000000, v10
	v_cmp_nle_f32_e64 s[16:17], |v9|, s71
	s_and_b64 s[14:15], s[8:9], s[14:15]
	v_cndmask_b32_e32 v10, v220, v47, vcc
	v_mul_f32_e64 v47, |v9|, -v147
	v_cndmask_b32_e64 v9, 0, 1, s[14:15]
	s_or_b64 vcc, s[8:9], s[16:17]
	v_cndmask_b32_e32 v9, v119, v9, vcc
	v_and_b32_e32 v9, 1, v9
	v_fmac_f32_e32 v47, 0x3e000000, v11
	v_cmp_eq_u32_e32 vcc, 1, v9
	s_nop 1
	v_cndmask_b32_e32 v47, v220, v47, vcc
	v_max3_f32 v8, v8, v10, v47
	v_mov_b32_e32 v9, v8
	s_waitcnt lgkmcnt(0)
	s_nop 1
	v_permlane16_swap_b32_e32 v9, v8
	v_max_f32_e32 v8, v8, v9
	v_mov_b32_e32 v9, v8
	s_waitcnt lgkmcnt(0)
	s_nop 1
	v_permlane32_swap_b32_e32 v9, v8
	v_max_f32_e32 v8, v8, v9
	v_mul_f32_e32 v119, 0xbfb8aa3b, v8
	v_fmamk_f32 v9, v100, 0x3fb8aa3b, v119
	v_fmamk_f32 v101, v103, 0x3fb8aa3b, v119
	v_fmamk_f32 v96, v96, 0x3fb8aa3b, v119
	v_exp_f32_e32 v9, v9
	v_fmamk_f32 v97, v97, 0x3fb8aa3b, v119
	v_fmamk_f32 v98, v98, 0x3fb8aa3b, v119
	v_fmamk_f32 v11, v102, 0x3fb8aa3b, v119
	v_fmamk_f32 v99, v99, 0x3fb8aa3b, v119
	v_fmamk_f32 v92, v92, 0x3fb8aa3b, v119
	v_exp_f32_e32 v11, v11
	v_fmamk_f32 v94, v94, 0x3fb8aa3b, v119
	v_exp_f32_e32 v101, v101
	v_mov_b32_e32 v100, v11
	v_add_f32_e32 v11, v9, v100
	v_fmamk_f32 v102, v104, 0x3fb8aa3b, v119
	v_add_f32_e32 v11, v101, v11
	v_fmamk_f32 v95, v95, 0x3fb8aa3b, v119
	v_exp_f32_e32 v102, v102
	v_fmamk_f32 v88, v88, 0x3fb8aa3b, v119
	v_exp_f32_e32 v96, v96
	v_add_f32_e32 v11, v102, v11
	v_exp_f32_e32 v97, v97
	v_add_f32_e32 v11, v96, v11
	v_exp_f32_e32 v98, v98
	v_add_f32_e32 v11, v97, v11
	v_exp_f32_e32 v99, v99
	v_add_f32_e32 v11, v98, v11
	v_exp_f32_e32 v92, v92
	v_add_f32_e32 v103, v99, v11
	v_mov_b32_e32 v11, v92
	v_fmamk_f32 v92, v93, 0x3fb8aa3b, v119
	v_add_f32_e32 v103, v11, v103
	v_fmamk_f32 v89, v89, 0x3fb8aa3b, v119
	v_exp_f32_e32 v92, v92
	v_fmamk_f32 v90, v90, 0x3fb8aa3b, v119
	v_exp_f32_e32 v94, v94
	v_add_f32_e32 v103, v92, v103
	v_mov_b32_e32 v93, v94
	v_add_f32_e32 v94, v93, v103
	v_fmamk_f32 v91, v91, 0x3fb8aa3b, v119
	v_exp_f32_e32 v95, v95
	v_fmamk_f32 v84, v84, 0x3fb8aa3b, v119
	v_fmamk_f32 v85, v85, 0x3fb8aa3b, v119
	v_exp_f32_e32 v104, v88
	v_mov_b32_e32 v88, v95
	v_add_f32_e32 v95, v88, v94
	v_mov_b32_e32 v94, v104
	v_fmamk_f32 v86, v86, 0x3fb8aa3b, v119
	v_exp_f32_e32 v89, v89
	v_fmamk_f32 v87, v87, 0x3fb8aa3b, v119
	v_exp_f32_e32 v90, v90
	v_fmamk_f32 v80, v80, 0x3fb8aa3b, v119
	v_exp_f32_e32 v91, v91
	v_fmamk_f32 v81, v81, 0x3fb8aa3b, v119
	v_exp_f32_e32 v84, v84
	v_add_f32_e32 v95, v94, v95
	v_exp_f32_e32 v85, v85
	v_add_f32_e32 v95, v89, v95
	v_fmamk_f32 v82, v82, 0x3fb8aa3b, v119
	v_exp_f32_e32 v104, v86
	v_mov_b32_e32 v86, v85
	v_mov_b32_e32 v85, v104
	v_add_f32_e32 v95, v90, v95
	v_exp_f32_e32 v87, v87
	v_add_f32_e32 v95, v91, v95
	v_add_f32_e32 v95, v84, v95
	v_exp_f32_e32 v104, v80
	v_mov_b32_e32 v80, v87
	v_mov_b32_e32 v87, v104
	v_add_f32_e32 v95, v86, v95
	v_exp_f32_e32 v81, v81
	v_add_f32_e32 v95, v85, v95
	v_exp_f32_e32 v82, v82
	v_add_f32_e32 v95, v80, v95
	v_add_f32_e32 v95, v87, v95
	v_fmamk_f32 v83, v83, 0x3fb8aa3b, v119
	v_add_f32_e32 v95, v81, v95
	v_add_f32_e32 v103, v82, v95
	v_fmamk_f32 v76, v76, 0x3fb8aa3b, v119
	v_exp_f32_e32 v83, v83
	v_fmamk_f32 v77, v77, 0x3fb8aa3b, v119
	v_exp_f32_e32 v76, v76
	v_mov_b32_e32 v95, v83
	v_add_f32_e32 v83, v95, v103
	v_fmamk_f32 v78, v78, 0x3fb8aa3b, v119
	v_exp_f32_e32 v77, v77
	v_fmamk_f32 v79, v79, 0x3fb8aa3b, v119
	v_exp_f32_e32 v78, v78
	v_fmamk_f32 v72, v72, 0x3fb8aa3b, v119
	v_exp_f32_e32 v79, v79
	v_add_f32_e32 v83, v76, v83
	v_exp_f32_e32 v72, v72
	v_add_f32_e32 v83, v77, v83
	v_add_f32_e32 v83, v78, v83
	v_add_f32_e32 v103, v79, v83
	v_fmamk_f32 v73, v73, 0x3fb8aa3b, v119
	v_mov_b32_e32 v83, v72
	v_add_f32_e32 v72, v83, v103
	v_fmamk_f32 v104, v105, 0x3fb8aa3b, v119
	v_exp_f32_e32 v73, v73
	v_fmamk_f32 v106, v106, 0x3fb8aa3b, v119
; __device__ void attn_mfma(const Params& p, int l, const bf16_t* proj, bf16_t* y0, LAS unsigned char* lds) {
;     ...
;                 for (int r = 0; r < 4; ++r) { const float pr = exp2f(fmaf(sacc[kt][r], 1.44269504f, -mxl)); sacc[kt][r] = pr; sum += pr; }
	v_exp_f32_e32 v104, v104
	v_mov_b32_e32 v103, v73
	v_add_f32_e32 v72, v103, v72
	v_fmamk_f32 v73, v107, 0x3fb8aa3b, v119
	v_add_f32_e32 v72, v104, v72
	v_fmamk_f32 v75, v75, 0x3fb8aa3b, v119
	v_exp_f32_e32 v73, v73
	v_fmamk_f32 v74, v74, 0x3fb8aa3b, v119
	v_exp_f32_e32 v106, v106
	v_mov_b32_e32 v105, v73
	v_add_f32_e32 v73, v105, v72
	v_mov_b32_e32 v72, v106
	v_add_f32_e32 v73, v72, v73
	v_exp_f32_e32 v75, v75
	v_fmamk_f32 v71, v71, 0x3fb8aa3b, v119
	v_fmamk_f32 v70, v70, 0x3fb8aa3b, v119
	v_exp_f32_e32 v107, v74
	v_mov_b32_e32 v74, v75
	v_add_f32_e32 v75, v74, v73
	v_mov_b32_e32 v73, v107
	v_fmamk_f32 v69, v69, 0x3fb8aa3b, v119
	v_exp_f32_e32 v71, v71
	v_fmamk_f32 v68, v68, 0x3fb8aa3b, v119
	v_fmamk_f32 v67, v67, 0x3fb8aa3b, v119
	v_exp_f32_e32 v107, v70
	v_mov_b32_e32 v70, v71
	v_mov_b32_e32 v71, v107
	v_fmamk_f32 v66, v66, 0x3fb8aa3b, v119
	v_exp_f32_e32 v69, v69
	v_fmamk_f32 v65, v65, 0x3fb8aa3b, v119
	v_fmamk_f32 v64, v64, 0x3fb8aa3b, v119
	v_exp_f32_e32 v107, v68
	v_mov_b32_e32 v68, v69
	v_mov_b32_e32 v69, v107
	v_fmamk_f32 v63, v63, 0x3fb8aa3b, v119
	v_exp_f32_e32 v67, v67
	v_fmamk_f32 v62, v62, 0x3fb8aa3b, v119
	v_exp_f32_e32 v66, v66
	v_fmamk_f32 v61, v61, 0x3fb8aa3b, v119
	v_exp_f32_e32 v65, v65
	v_fmamk_f32 v60, v60, 0x3fb8aa3b, v119
	v_fmamk_f32 v59, v59, 0x3fb8aa3b, v119
	v_exp_f32_e32 v107, v64
	v_mov_b32_e32 v64, v65
	v_mov_b32_e32 v65, v107
	v_fmamk_f32 v58, v58, 0x3fb8aa3b, v119
	v_exp_f32_e32 v63, v63
	v_fmamk_f32 v57, v57, 0x3fb8aa3b, v119
	v_fmamk_f32 v56, v56, 0x3fb8aa3b, v119
	v_exp_f32_e32 v107, v62
	v_mov_b32_e32 v62, v63
	v_mov_b32_e32 v63, v107
	v_fmamk_f32 v55, v55, 0x3fb8aa3b, v119
	v_exp_f32_e32 v61, v61
	v_fmamk_f32 v54, v54, 0x3fb8aa3b, v119
	v_fmamk_f32 v53, v53, 0x3fb8aa3b, v119
	v_exp_f32_e32 v107, v60
	v_mov_b32_e32 v60, v61
	v_mov_b32_e32 v61, v107
	v_fmamk_f32 v52, v52, 0x3fb8aa3b, v119
	v_exp_f32_e32 v59, v59
	v_fmamk_f32 v51, v51, 0x3fb8aa3b, v119
	v_exp_f32_e32 v58, v58
	v_fmamk_f32 v50, v50, 0x3fb8aa3b, v119
	v_exp_f32_e32 v57, v57
	v_fmamk_f32 v49, v49, 0x3fb8aa3b, v119
	v_exp_f32_e32 v56, v56
	v_fmamk_f32 v48, v48, 0x3fb8aa3b, v119
	v_exp_f32_e32 v55, v55
	v_fmamk_f32 v46, v46, 0x3fb8aa3b, v119
	v_fmamk_f32 v45, v45, 0x3fb8aa3b, v119
	v_exp_f32_e32 v107, v54
	v_mov_b32_e32 v54, v55
	v_mov_b32_e32 v55, v107
	v_fmamk_f32 v44, v44, 0x3fb8aa3b, v119
	v_exp_f32_e32 v53, v53
	v_fmamk_f32 v41, v41, 0x3fb8aa3b, v119
	v_fmamk_f32 v40, v40, 0x3fb8aa3b, v119
	v_exp_f32_e32 v107, v52
	v_mov_b32_e32 v52, v53
	v_mov_b32_e32 v53, v107
	v_fmamk_f32 v36, v36, 0x3fb8aa3b, v119
	v_exp_f32_e32 v51, v51
	v_fmamk_f32 v37, v37, 0x3fb8aa3b, v119
	v_exp_f32_e32 v50, v50
	v_fmamk_f32 v38, v38, 0x3fb8aa3b, v119
	v_exp_f32_e32 v49, v49
	v_fmamk_f32 v39, v39, 0x3fb8aa3b, v119
	v_fmamk_f32 v32, v32, 0x3fb8aa3b, v119
	v_exp_f32_e32 v107, v48
	v_mov_b32_e32 v48, v49
	v_mov_b32_e32 v49, v107
	v_fmamk_f32 v33, v33, 0x3fb8aa3b, v119
	v_exp_f32_e32 v46, v46
	v_fmamk_f32 v34, v34, 0x3fb8aa3b, v119
	v_fmamk_f32 v35, v35, 0x3fb8aa3b, v119
	v_exp_f32_e32 v107, v45
	v_mov_b32_e32 v45, v46
	v_mov_b32_e32 v46, v107
	v_fmamk_f32 v28, v28, 0x3fb8aa3b, v119
	v_exp_f32_e32 v44, v44
	v_fmamk_f32 v29, v29, 0x3fb8aa3b, v119
	v_fmamk_f32 v30, v30, 0x3fb8aa3b, v119
	v_exp_f32_e32 v107, v41
	v_mov_b32_e32 v41, v44
	v_mov_b32_e32 v44, v107
	v_add_f32_e32 v75, v73, v75
	v_exp_f32_e32 v40, v40
	v_add_f32_e32 v75, v70, v75
	v_exp_f32_e32 v36, v36
	v_add_f32_e32 v75, v71, v75
	v_exp_f32_e32 v37, v37
	v_add_f32_e32 v75, v68, v75
	v_add_f32_e32 v75, v69, v75
	v_exp_f32_e32 v107, v38
	v_mov_b32_e32 v38, v37
	v_mov_b32_e32 v37, v107
	v_fmamk_f32 v31, v31, 0x3fb8aa3b, v119
	v_exp_f32_e32 v39, v39
	v_add_f32_e32 v75, v67, v75
	v_add_f32_e32 v75, v66, v75
	v_exp_f32_e32 v107, v32
	v_mov_b32_e32 v32, v39
	v_mov_b32_e32 v39, v107
	v_add_f32_e32 v75, v64, v75
	v_exp_f32_e32 v33, v33
	v_fmamk_f32 v24, v24, 0x3fb8aa3b, v119
	v_exp_f32_e32 v34, v34
	v_add_f32_e32 v75, v65, v75
	v_exp_f32_e32 v35, v35
	v_add_f32_e32 v75, v62, v75
	v_exp_f32_e32 v28, v28
	v_add_f32_e32 v75, v63, v75
	v_exp_f32_e32 v29, v29
	v_add_f32_e32 v75, v60, v75
	v_exp_f32_e32 v30, v30
	v_fmamk_f32 v25, v25, 0x3fb8aa3b, v119
	v_exp_f32_e32 v31, v31
	v_add_f32_e32 v75, v61, v75
	v_add_f32_e32 v75, v59, v75
	v_exp_f32_e32 v107, v24
	v_mov_b32_e32 v24, v31
	v_fmamk_f32 v26, v26, 0x3fb8aa3b, v119
	v_add_f32_e32 v75, v58, v75
	v_add_f32_e32 v75, v57, v75
	v_mov_b32_e32 v31, v107
	v_add_f32_e32 v75, v56, v75
	v_exp_f32_e32 v25, v25
	v_add_f32_e32 v75, v54, v75
	v_exp_f32_e32 v26, v26
	v_add_f32_e32 v75, v55, v75
	v_add_f32_e32 v75, v52, v75
	v_fmamk_f32 v27, v27, 0x3fb8aa3b, v119
	v_add_f32_e32 v75, v53, v75
	v_add_f32_e32 v75, v51, v75
	v_fmamk_f32 v20, v20, 0x3fb8aa3b, v119
	v_add_f32_e32 v75, v50, v75
	v_add_f32_e32 v75, v48, v75
	v_add_f32_e32 v75, v49, v75
	v_exp_f32_e32 v27, v27
	v_add_f32_e32 v75, v45, v75
	v_exp_f32_e32 v20, v20
	v_add_f32_e32 v75, v46, v75
	v_add_f32_e32 v75, v41, v75
	v_fmamk_f32 v21, v21, 0x3fb8aa3b, v119
	v_add_f32_e32 v75, v44, v75
	v_add_f32_e32 v75, v40, v75
	v_add_f32_e32 v75, v36, v75
	v_add_f32_e32 v75, v38, v75
	v_exp_f32_e32 v21, v21
	v_fmamk_f32 v22, v22, 0x3fb8aa3b, v119
	v_add_f32_e32 v75, v37, v75
	v_add_f32_e32 v75, v32, v75
	v_add_f32_e32 v75, v39, v75
	v_fmamk_f32 v23, v23, 0x3fb8aa3b, v119
	v_add_f32_e32 v75, v33, v75
	v_exp_f32_e32 v107, v22
	v_mov_b32_e32 v22, v21
	v_add_f32_e32 v75, v34, v75
	v_add_f32_e32 v75, v35, v75
	v_fmamk_f32 v16, v16, 0x3fb8aa3b, v119
	v_add_f32_e32 v75, v28, v75
	v_exp_f32_e32 v23, v23
	v_add_f32_e32 v75, v29, v75
	v_mov_b32_e32 v21, v107
	v_add_f32_e32 v75, v30, v75
	v_add_f32_e32 v75, v24, v75
	v_exp_f32_e32 v107, v16
; #define LAS __attribute__((address_space(3)))
; __device__ __forceinline__ unsigned cvt_pk_bf16_mfma(float lo, float hi) { const f32x2 v = {lo, hi}; return __builtin_bit_cast(unsigned, __builtin_convertvector(v, bf16v2_t)); }
; __device__ void attn_mfma(const Params& p, int l, const bf16_t* proj, bf16_t* y0, LAS unsigned char* lds) {
;     ...
;                 for (int r = 0; r < 4; ++r) { const float pr = exp2f(fmaf(sacc[kt][r], 1.44269504f, -mxl)); sacc[kt][r] = pr; sum += pr; }
;             sum += __shfl_xor(sum, 16); sum += __shfl_xor(sum, 32);
;             const float inv = 1.0f / (sum + __expf(sink - mx));
;             f32x4 oacc[4];
; #pragma unroll
;             for (int dt = 0; dt < 4; ++dt) oacc[dt] = (f32x4){0.f, 0.f, 0.f, 0.f};
; #pragma unroll
;             for (int i = 0; i < 12; ++i) {
;                 u32x4 pw; pw.x = cvt_pk_bf16_mfma(sacc[2 * i][0], sacc[2 * i][1]); pw.y = cvt_pk_bf16_mfma(sacc[2 * i][2], sacc[2 * i][3]); pw.z = cvt_pk_bf16_mfma(sacc[2 * i + 1][0], sacc[2 * i + 1][1]); pw.w = cvt_pk_bf16_mfma(sacc[2 * i + 1][2], sacc[2 * i + 1][3]);
;                 const bf16x8 pf = __builtin_bit_cast(bf16x8, pw);
; #pragma unroll
;                 for (int dt = 0; dt < 4; ++dt) { const LAS bf16_t* vp = Vt + (dt * 16 + fr) * VP + 32 * i + 4 * g;
;                     const u32x2 lo = *(const LAS u32x2*)vp, hi = *(const LAS u32x2*)(vp + 16);
;                     u32x4 vw; vw.x = lo.x; vw.y = lo.y; vw.z = hi.x; vw.w = hi.y;
;                     oacc[dt] = __builtin_amdgcn_mfma_f32_16x16x32_bf16(__builtin_bit_cast(bf16x8, vw), pf, oacc[dt], 0, 0, 0); }
;                 if (i & 1) __builtin_amdgcn_sched_barrier(0); }
	v_fmamk_f32 v17, v17, 0x3fb8aa3b, v119
	v_add_f32_e32 v75, v31, v75
	v_mov_b32_e32 v16, v23
	v_add_f32_e32 v75, v25, v75
	v_fmamk_f32 v18, v18, 0x3fb8aa3b, v119
	v_add_f32_e32 v75, v26, v75
	v_add_f32_e32 v75, v27, v75
	v_mov_b32_e32 v23, v107
	v_add_f32_e32 v75, v20, v75
	v_exp_f32_e32 v17, v17
	v_add_f32_e32 v75, v22, v75
	v_exp_f32_e32 v18, v18
	v_add_f32_e32 v75, v21, v75
	v_add_f32_e32 v75, v16, v75
	v_add_f32_e32 v75, v23, v75
	v_fmamk_f32 v19, v19, 0x3fb8aa3b, v119
	v_add_f32_e32 v75, v17, v75
	v_add_f32_e32 v106, v18, v75
	v_fmamk_f32 v12, v12, 0x3fb8aa3b, v119
	v_exp_f32_e32 v19, v19
	v_fmamk_f32 v13, v13, 0x3fb8aa3b, v119
	v_exp_f32_e32 v12, v12
	v_mov_b32_e32 v75, v19
	v_add_f32_e32 v19, v75, v106
	v_fmamk_f32 v14, v14, 0x3fb8aa3b, v119
	v_exp_f32_e32 v13, v13
	v_fmamk_f32 v15, v15, 0x3fb8aa3b, v119
	v_exp_f32_e32 v14, v14
	v_fmamk_f32 v42, v42, 0x3fb8aa3b, v119
	v_exp_f32_e32 v15, v15
	v_add_f32_e32 v19, v12, v19
	v_exp_f32_e32 v42, v42
	v_add_f32_e32 v19, v13, v19
	v_add_f32_e32 v19, v14, v19
	v_add_f32_e32 v106, v15, v19
	v_fmamk_f32 v43, v43, 0x3fb8aa3b, v119
	v_mov_b32_e32 v19, v42
	v_add_f32_e32 v42, v19, v106
	v_fmamk_f32 v10, v10, 0x3fb8aa3b, v119
	v_exp_f32_e32 v43, v43
	v_fmac_f32_e32 v119, 0x3fb8aa3b, v47
	v_add_u32_e32 v47, 0xd800, v142
	v_exp_f32_e32 v107, v10
	v_mov_b32_e32 v10, v43
	v_add_f32_e32 v106, v10, v42
	v_mov_b32_e32 v42, v107
	v_cvt_pk_bf16_f32 v154, v9, v100
	v_add_u32_e32 v9, 0xd800, v143
	v_cvt_pk_bf16_f32 v156, v96, v97
	v_add_u32_e32 v43, 0xd800, v144
	v_add_u32_e32 v96, 0xd800, v145
	ds_read2_b64 v[150:153], v47 offset1:4
	v_cvt_pk_bf16_f32 v155, v101, v102
	ds_read2_b64 v[158:161], v9 offset1:4
	v_cvt_pk_bf16_f32 v157, v98, v99
	ds_read2_b64 v[98:101], v43 offset1:4
	ds_read2_b64 v[162:165], v96 offset1:4
	ds_read2_b64 v[166:169], v47 offset0:8 offset1:12
	s_waitcnt lgkmcnt(4)
	v_mfma_f32_16x16x32_bf16 v[150:153], v[150:153], v[154:157], 0
	v_exp_f32_e32 v97, v119
	v_add_f32_e32 v102, v42, v106
	s_waitcnt lgkmcnt(3)
	v_mfma_f32_16x16x32_bf16 v[158:161], v[158:161], v[154:157], 0
	v_cvt_pk_bf16_f32 v170, v11, v92
	v_cvt_pk_bf16_f32 v171, v93, v88
	s_waitcnt lgkmcnt(2)
	v_mfma_f32_16x16x32_bf16 v[98:101], v[98:101], v[154:157], 0
	v_cvt_pk_bf16_f32 v172, v94, v89
	v_cvt_pk_bf16_f32 v173, v90, v91
	v_add_f32_e32 v102, v97, v102
	s_waitcnt lgkmcnt(1)
	v_mfma_f32_16x16x32_bf16 v[154:157], v[162:165], v[154:157], 0
	ds_read2_b64 v[162:165], v9 offset0:8 offset1:12
	ds_bpermute_b32 v106, v121, v102
	v_sub_f32_e32 v8, v146, v8
	s_waitcnt lgkmcnt(2)
	v_mfma_f32_16x16x32_bf16 v[88:91], v[166:169], v[170:173], v[150:153]
	v_mul_f32_e32 v8, 0x3fb8aa3b, v8
	v_exp_f32_e32 v8, v8
	s_waitcnt lgkmcnt(0)
	v_add_f32_e32 v11, v102, v106
	ds_read2_b64 v[150:153], v43 offset0:8 offset1:12
	v_mfma_f32_16x16x32_bf16 v[158:161], v[162:165], v[170:173], v[158:161]
	ds_read2_b64 v[162:165], v96 offset0:8 offset1:12
	v_mov_b32_e32 v92, v11
	s_waitcnt lgkmcnt(0)
	s_nop 1
	v_permlane32_swap_b32_e32 v92, v11
	v_add_f32_e32 v11, v11, v92
	v_mfma_f32_16x16x32_bf16 v[98:101], v[150:153], v[170:173], v[98:101]
	v_add_f32_e32 v106, v8, v11
	v_mfma_f32_16x16x32_bf16 v[150:153], v[162:165], v[170:173], v[154:157]
	v_cvt_pk_bf16_f32 v84, v84, v86
	v_cvt_pk_bf16_f32 v86, v87, v81
	v_cvt_pk_bf16_f32 v87, v82, v95
	ds_read2_b64 v[92:95], v43 offset0:16 offset1:20
	ds_read2_b64 v[154:157], v47 offset0:16 offset1:20
	v_cvt_pk_bf16_f32 v85, v85, v80
	ds_read2_b64 v[162:165], v9 offset0:16 offset1:20
	v_cvt_pk_bf16_f32 v76, v76, v77
	v_cvt_pk_bf16_f32 v77, v78, v79
	s_waitcnt lgkmcnt(2)
	v_mfma_f32_16x16x32_bf16 v[92:95], v[92:95], v[84:87], v[98:101]
	s_nop 2
	ds_read2_b64 v[98:101], v47 offset0:24 offset1:28
	v_cvt_pk_bf16_f32 v78, v83, v103
	v_cvt_pk_bf16_f32 v79, v104, v105
	s_waitcnt lgkmcnt(2)
	v_mfma_f32_16x16x32_bf16 v[88:91], v[154:157], v[84:87], v[88:91]
	s_waitcnt lgkmcnt(0)
	v_mfma_f32_16x16x32_bf16 v[80:83], v[98:101], v[76:79], v[88:91]
	ds_read2_b64 v[98:101], v43 offset0:24 offset1:28
	s_nop 4
	ds_read2_b64 v[88:91], v9 offset0:24 offset1:28
	v_mfma_f32_16x16x32_bf16 v[154:157], v[162:165], v[84:87], v[158:161]
	s_nop 2
	ds_read2_b64 v[158:161], v96 offset0:16 offset1:20
	s_waitcnt lgkmcnt(2)
	v_mfma_f32_16x16x32_bf16 v[92:95], v[98:101], v[76:79], v[92:95]
	ds_read2_b64 v[98:101], v96 offset0:24 offset1:28
	s_waitcnt lgkmcnt(1)
	v_mfma_f32_16x16x32_bf16 v[84:87], v[158:161], v[84:87], v[150:153]
	v_mfma_f32_16x16x32_bf16 v[88:91], v[88:91], v[76:79], v[154:157]
	s_waitcnt lgkmcnt(0)
	v_mfma_f32_16x16x32_bf16 v[76:79], v[98:101], v[76:79], v[84:87]
	s_nop 4
	ds_read2_b64 v[84:87], v47 offset0:32 offset1:36
	v_cvt_pk_bf16_f32 v98, v72, v74
	v_cvt_pk_bf16_f32 v99, v73, v70
	v_cvt_pk_bf16_f32 v100, v71, v68
	v_cvt_pk_bf16_f32 v101, v69, v67
	ds_read2_b64 v[102:105], v9 offset0:32 offset1:36
	v_cvt_pk_bf16_f32 v64, v66, v64
	v_cvt_pk_bf16_f32 v65, v65, v62
	v_cvt_pk_bf16_f32 v66, v63, v60
	s_waitcnt lgkmcnt(1)
	v_mfma_f32_16x16x32_bf16 v[68:71], v[84:87], v[98:101], v[80:83]
	v_cvt_pk_bf16_f32 v67, v61, v59
	s_nop 1
	ds_read2_b64 v[80:83], v43 offset0:32 offset1:36
	s_waitcnt lgkmcnt(1)
	v_mfma_f32_16x16x32_bf16 v[84:87], v[102:105], v[98:101], v[88:91]
	s_waitcnt lgkmcnt(0)
	v_mfma_f32_16x16x32_bf16 v[80:83], v[80:83], v[98:101], v[92:95]
	s_nop 2
	ds_read2_b64 v[92:95], v47 offset0:40 offset1:44
	ds_read2_b64 v[88:91], v96 offset0:32 offset1:36
	s_waitcnt lgkmcnt(0)
	v_mfma_f32_16x16x32_bf16 v[76:79], v[88:91], v[98:101], v[76:79]
	v_mfma_f32_16x16x32_bf16 v[60:63], v[92:95], v[64:67], v[68:71]
	s_nop 2
	ds_read2_b64 v[68:71], v9 offset0:40 offset1:44
	s_waitcnt lgkmcnt(0)
; #define LAS __attribute__((address_space(3)))
; __device__ __forceinline__ unsigned cvt_pk_bf16(float lo, float hi) { unsigned r; asm("v_cvt_pk_bf16_f32 %0, %1, %2" : "=v"(r) : "v"(lo), "v"(hi)); return r; }
; __device__ __forceinline__ unsigned cvt_pk_bf16_mfma(float lo, float hi) { const f32x2 v = {lo, hi}; return __builtin_bit_cast(unsigned, __builtin_convertvector(v, bf16v2_t)); }
; __device__ void attn_mfma(const Params& p, int l, const bf16_t* proj, bf16_t* y0, LAS unsigned char* lds) {
;     ...
;             const float inv = 1.0f / (sum + __expf(sink - mx));
;             f32x4 oacc[4];
; #pragma unroll
;             for (int dt = 0; dt < 4; ++dt) oacc[dt] = (f32x4){0.f, 0.f, 0.f, 0.f};
; #pragma unroll
;             for (int i = 0; i < 12; ++i) {
;                 u32x4 pw; pw.x = cvt_pk_bf16_mfma(sacc[2 * i][0], sacc[2 * i][1]); pw.y = cvt_pk_bf16_mfma(sacc[2 * i][2], sacc[2 * i][3]); pw.z = cvt_pk_bf16_mfma(sacc[2 * i + 1][0], sacc[2 * i + 1][1]); pw.w = cvt_pk_bf16_mfma(sacc[2 * i + 1][2], sacc[2 * i + 1][3]);
;                 const bf16x8 pf = __builtin_bit_cast(bf16x8, pw);
; #pragma unroll
;                 for (int dt = 0; dt < 4; ++dt) { const LAS bf16_t* vp = Vt + (dt * 16 + fr) * VP + 32 * i + 4 * g;
;                     const u32x2 lo = *(const LAS u32x2*)vp, hi = *(const LAS u32x2*)(vp + 16);
;                     u32x4 vw; vw.x = lo.x; vw.y = lo.y; vw.z = hi.x; vw.w = hi.y;
;                     oacc[dt] = __builtin_amdgcn_mfma_f32_16x16x32_bf16(__builtin_bit_cast(bf16x8, vw), pf, oacc[dt], 0, 0, 0); }
;                 if (i & 1) __builtin_amdgcn_sched_barrier(0); }
; #pragma unroll
;             for (int dt = 0; dt < 4; ++dt) { u32x2 w; w.x = cvt_pk_bf16(oacc[dt][0] * inv, oacc[dt][1] * inv); w.y = cvt_pk_bf16(oacc[dt][2] * inv, oacc[dt][3] * inv);
;                 *(u32x2*)(y0 + (size_t)t * 512 + hq * 64 + dt * 16 + 4 * g) = w; }
;         }
	v_mfma_f32_16x16x32_bf16 v[68:71], v[68:71], v[64:67], v[84:87]
	s_nop 2
	ds_read2_b64 v[84:87], v43 offset0:40 offset1:44
	s_waitcnt lgkmcnt(0)
	v_mfma_f32_16x16x32_bf16 v[80:83], v[84:87], v[64:67], v[80:83]
	ds_read2_b64 v[84:87], v96 offset0:40 offset1:44
	s_waitcnt lgkmcnt(0)
	v_mfma_f32_16x16x32_bf16 v[64:67], v[84:87], v[64:67], v[76:79]
	s_nop 2
	ds_read2_b64 v[76:79], v47 offset0:48 offset1:52
	ds_read2_b64 v[88:91], v9 offset0:48 offset1:52
	v_cvt_pk_bf16_f32 v84, v58, v57
	v_cvt_pk_bf16_f32 v85, v56, v54
	v_cvt_pk_bf16_f32 v86, v55, v52
	v_cvt_pk_bf16_f32 v87, v53, v51
	ds_read2_b64 v[56:59], v43 offset0:48 offset1:52
	v_cvt_pk_bf16_f32 v48, v50, v48
	v_cvt_pk_bf16_f32 v49, v49, v45
	s_waitcnt lgkmcnt(2)
	v_mfma_f32_16x16x32_bf16 v[52:55], v[76:79], v[84:87], v[60:63]
	v_cvt_pk_bf16_f32 v50, v46, v41
	v_cvt_pk_bf16_f32 v51, v44, v40
	ds_read2_b64 v[76:79], v47 offset0:56 offset1:60
	s_waitcnt lgkmcnt(2)
	v_mfma_f32_16x16x32_bf16 v[60:63], v[88:91], v[84:87], v[68:71]
	s_nop 2
	ds_read2_b64 v[68:71], v96 offset0:48 offset1:52
	s_waitcnt lgkmcnt(0)
	v_mfma_f32_16x16x32_bf16 v[64:67], v[68:71], v[84:87], v[64:67]
	ds_read2_b64 v[68:71], v9 offset0:56 offset1:60
	s_waitcnt lgkmcnt(0)
	v_mfma_f32_16x16x32_bf16 v[60:63], v[68:71], v[48:51], v[60:63]
	ds_read2_b64 v[68:71], v43 offset0:56 offset1:60
	v_mfma_f32_16x16x32_bf16 v[56:59], v[56:59], v[84:87], v[80:83]
	s_waitcnt lgkmcnt(0)
	v_mfma_f32_16x16x32_bf16 v[56:59], v[68:71], v[48:51], v[56:59]
	ds_read2_b64 v[68:71], v96 offset0:56 offset1:60
	v_mfma_f32_16x16x32_bf16 v[52:55], v[76:79], v[48:51], v[52:55]
	s_waitcnt lgkmcnt(0)
	v_mfma_f32_16x16x32_bf16 v[48:51], v[68:71], v[48:51], v[64:67]
	s_nop 2
	ds_read2_b64 v[64:67], v47 offset0:64 offset1:68
	v_cvt_pk_bf16_f32 v36, v36, v38
	v_cvt_pk_bf16_f32 v37, v37, v32
	v_cvt_pk_bf16_f32 v38, v39, v33
	v_cvt_pk_bf16_f32 v39, v34, v35
	ds_read2_b64 v[68:71], v9 offset0:64 offset1:68
	v_cvt_pk_bf16_f32 v28, v28, v29
	v_cvt_pk_bf16_f32 v29, v30, v24
	v_cvt_pk_bf16_f32 v30, v31, v25
	s_waitcnt lgkmcnt(1)
	v_mfma_f32_16x16x32_bf16 v[32:35], v[64:67], v[36:39], v[52:55]
	ds_read2_b64 v[64:67], v96 offset0:64 offset1:68
	v_cvt_pk_bf16_f32 v31, v26, v27
	s_nop 0
	ds_read2_b64 v[52:55], v43 offset0:64 offset1:68
	s_waitcnt lgkmcnt(2)
	v_mfma_f32_16x16x32_bf16 v[60:63], v[68:71], v[36:39], v[60:63]
	s_waitcnt lgkmcnt(0)
	v_mfma_f32_16x16x32_bf16 v[52:55], v[52:55], v[36:39], v[56:59]
	s_nop 2
	ds_read2_b64 v[56:59], v47 offset0:72 offset1:76
	v_mfma_f32_16x16x32_bf16 v[36:39], v[64:67], v[36:39], v[48:51]
	s_nop 2
	ds_read2_b64 v[48:51], v43 offset0:72 offset1:76
	s_waitcnt lgkmcnt(1)
	v_mfma_f32_16x16x32_bf16 v[24:27], v[56:59], v[28:31], v[32:35]
	s_nop 2
	ds_read2_b64 v[32:35], v9 offset0:72 offset1:76
	s_waitcnt lgkmcnt(1)
	v_mfma_f32_16x16x32_bf16 v[48:51], v[48:51], v[28:31], v[52:55]
	s_nop 2
	ds_read2_b64 v[52:55], v96 offset0:72 offset1:76
	s_waitcnt lgkmcnt(1)
	v_mfma_f32_16x16x32_bf16 v[32:35], v[32:35], v[28:31], v[60:63]
	s_waitcnt lgkmcnt(0)
	v_mfma_f32_16x16x32_bf16 v[28:31], v[52:55], v[28:31], v[36:39]
	s_nop 2
	ds_read2_b64 v[36:39], v47 offset0:80 offset1:84
	ds_read2_b64 v[52:55], v9 offset0:80 offset1:84
	v_cvt_pk_bf16_f32 v20, v20, v22
	v_cvt_pk_bf16_f32 v21, v21, v16
	v_cvt_pk_bf16_f32 v22, v23, v17
	v_cvt_pk_bf16_f32 v23, v18, v75
	ds_read2_b64 v[44:47], v47 offset0:88 offset1:92
	v_cvt_pk_bf16_f32 v12, v12, v13
	v_cvt_pk_bf16_f32 v13, v14, v15
	s_waitcnt lgkmcnt(2)
	v_mfma_f32_16x16x32_bf16 v[24:27], v[36:39], v[20:23], v[24:27]
	ds_read2_b64 v[36:39], v43 offset0:80 offset1:84
	v_cvt_pk_bf16_f32 v14, v19, v10
	ds_read2_b64 v[8:11], v9 offset0:88 offset1:92
	s_waitcnt lgkmcnt(3)
	v_mfma_f32_16x16x32_bf16 v[32:35], v[52:55], v[20:23], v[32:35]
	ds_read2_b64 v[52:55], v96 offset0:80 offset1:84
	v_cvt_pk_bf16_f32 v15, v42, v97
	s_waitcnt lgkmcnt(2)
	v_mfma_f32_16x16x32_bf16 v[36:39], v[36:39], v[20:23], v[48:51]
	s_waitcnt lgkmcnt(0)
	v_mfma_f32_16x16x32_bf16 v[20:23], v[52:55], v[20:23], v[28:31]
	v_mfma_f32_16x16x32_bf16 v[16:19], v[44:47], v[12:15], v[24:27]
	s_nop 1
	ds_read2_b64 v[28:31], v96 offset0:88 offset1:92
	ds_read2_b64 v[24:27], v43 offset0:88 offset1:92
	v_mfma_f32_16x16x32_bf16 v[8:11], v[8:11], v[12:15], v[32:35]
	s_waitcnt lgkmcnt(0)
	v_mfma_f32_16x16x32_bf16 v[24:27], v[24:27], v[12:15], v[36:39]
	v_mfma_f32_16x16x32_bf16 v[12:15], v[28:31], v[12:15], v[20:23]
	s_nop 2
	v_div_scale_f32 v20, s[14:15], v106, v106, 1.0
	v_rcp_f32_e32 v21, v20
	v_div_scale_f32 v22, vcc, 1.0, v106, 1.0
	v_ashrrev_i32_e32 v119, 31, v118
	v_fma_f32 v23, -v20, v21, 1.0
	v_fmac_f32_e32 v21, v23, v21
	v_mul_f32_e32 v23, v22, v21
	v_fma_f32 v28, -v20, v23, v22
	v_fmac_f32_e32 v23, v28, v21
	v_fma_f32 v20, -v20, v23, v22
	v_div_fmas_f32 v20, v20, v21, v23
	v_div_fixup_f32 v22, v20, v106, 1.0
	v_mul_f32_e32 v8, v22, v8
	v_mul_f32_e32 v9, v22, v9
	v_lshlrev_b64 v[20:21], 10, v[118:119]
	v_cvt_pk_bf16_f32 v8, v8, v9
	v_mul_f32_e32 v9, v22, v10
	v_lshl_add_u64 v[20:21], v[116:117], 0, v[20:21]
	v_mul_f32_e32 v10, v22, v11
	v_cvt_pk_bf16_f32 v9, v9, v10
	global_store_dwordx2 v[20:21], v[8:9], off offset:32
	v_mul_f32_e32 v8, v22, v24
	v_mul_f32_e32 v9, v22, v25
	v_cvt_pk_bf16_f32 v8, v8, v9
	v_mul_f32_e32 v9, v22, v26
	v_mul_f32_e32 v10, v22, v27
	v_cvt_pk_bf16_f32 v9, v9, v10
	global_store_dwordx2 v[20:21], v[8:9], off offset:64
	v_mul_f32_e32 v8, v22, v12
	v_mul_f32_e32 v9, v22, v13
	v_cvt_pk_bf16_f32 v8, v8, v9
	v_mul_f32_e32 v9, v22, v14
	v_mul_f32_e32 v10, v22, v15
	v_cvt_pk_bf16_f32 v9, v9, v10
	v_mul_f32_e32 v16, v22, v16
	v_mul_f32_e32 v17, v22, v17
	global_store_dwordx2 v[20:21], v[8:9], off offset:96
	s_add_i32 s12, s12, 16
	s_waitcnt vmcnt(3)
	v_mov_b64_e32 v[10:11], v[6:7]
	v_mov_b64_e32 v[102:103], v[2:3]
	v_cvt_pk_bf16_f32 v16, v16, v17
	v_mul_f32_e32 v17, v22, v18
	s_cmp_eq_u32 s12, 64
	v_mov_b64_e32 v[8:9], v[4:5]
	v_mov_b64_e32 v[100:101], v[0:1]
	v_mul_f32_e32 v18, v22, v19
	v_cvt_pk_bf16_f32 v17, v17, v18
	global_store_dwordx2 v[20:21], v[16:17], off
	s_cbranch_scc0 .LBB0_478
	s_add_i32 s11, s11, s59
	s_cmpk_gt_i32 s11, 0xff
	s_cbranch_scc0 .LBB0_459
